# phase 3 row pass hand-written (8 contiguous rows per wave of the workgroup's own M-tile quarter, loads two rows ahead), grid barriers unchanged
# baseline (speedup 1.0000x reference)
;     __device__ __forceinline__ float* out() const { return (float*)ptr(36); }
; __device__ __forceinline__ const float* xrow_ptr(const Ctx& p, int row) { return row < MPR ? p.in(0) + (size_t)row * DM : p.in(1) + (size_t)(row - MPR) * DM; }
; __device__ __forceinline__ void phase_rowpass(const Ctx& p, const float* F, int base_is_x, float alpha, const float* gpost, const float* gnext, bf16_t* XN, const float* PART, int nsplit) {
;     const int tid = threadIdx.x, lane = tid & 63, wave = __builtin_amdgcn_readfirstlane(tid >> 6);
;     const int gw = blockIdx.x * 8 + wave, NGW = gridDim.x * 8;
;     float* H = p.out() + O_Y;
;     auto loadrow = [&](int m, f32x4 (&f)[4], f32x4 (&b)[4]) {
;         const f32x4* fr = (const f32x4*)(F + (size_t)m * DM) + lane;
;         const f32x4* br = (const f32x4*)(base_is_x ? xrow_ptr(p, m) : H + (size_t)m * DM) + lane;
; #pragma unroll
;         for (int j = 0; j < 4; ++j) { b[j] = br[64 * j];
;             if (m < MPR) f[j] = fr[64 * j];
;             else { f[j] = (f32x4){0.f, 0.f, 0.f, 0.f};
;                 for (int ks = 0; ks < nsplit; ++ks) f[j] = f[j] + ((const f32x4*)(PART + ((size_t)ks * 128 + (m - MPR)) * DM))[lane + 64 * j]; } }
;     };
;     f32x4 gp[4], gn[4];
; #pragma unroll
;     for (int j = 0; j < 4; ++j) { gp[j] = ((const f32x4*)gpost)[lane + 64 * j]; gn[j] = gnext ? ((const f32x4*)gnext)[lane + 64 * j] : (f32x4){0.f, 0.f, 0.f, 0.f}; }
;     f32x4 f[4], b[4], f2[4], b2[4];
;     if (gw < MR) loadrow(gw, f, b);
;     for (int m = gw; m < MR; m += NGW) {
;         const bool more = m + NGW < MR;
;         if (more) loadrow(m + NGW, f2, b2);
;         float s = 0.f;
; #pragma unroll
;         for (int j = 0; j < 4; ++j) s += (f[j].x * f[j].x + f[j].y * f[j].y) + (f[j].z * f[j].z + f[j].w * f[j].w);
;         const float rs = alpha / sqrtf(wave_sum_fast(s) * (1.f / DM) + EPS);
.LBB0_389:
.Lfrp3:
	v_mov_b32_e32 v0, 0x23520
	v_mov_b32_e32 v1, 0x23448
	ds_read_b64 v[2:3], v0
	ds_read_b64 v[4:5], v1
	v_mov_b32_e32 v1, 0x23450
	ds_read_b64 v[6:7], v1
	v_mov_b32_e32 v1, 0x23400
	ds_read_b128 v[8:11], v1
	v_readfirstlane_b32 s2, v180
	s_waitcnt lgkmcnt(0)
	v_readfirstlane_b32 s8, v2
	v_readfirstlane_b32 s9, v3
	v_readfirstlane_b32 s10, v4
	v_readfirstlane_b32 s11, v5
	v_readfirstlane_b32 s12, v6
	v_readfirstlane_b32 s13, v7
	v_readfirstlane_b32 s14, v8
	v_readfirstlane_b32 s15, v9
	v_readfirstlane_b32 s16, v10
	v_readfirstlane_b32 s17, v11
	s_nop 4
	s_lshr_b32 s20, s2, 6
	v_and_b32_e32 v0, 63, v180
	v_lshlrev_b32_e32 v144, 4, v0
	v_lshlrev_b32_e32 v145, 3, v0
	v_mov_b32_e32 v146, 0x358637bd
	v_mov_b32_e32 v147, 0x260
	s_mov_b32 s33, 0xf800000
	global_load_dwordx4 v[112:115], v144, s[10:11] offset:0
	global_load_dwordx4 v[116:119], v144, s[10:11] offset:1024
	global_load_dwordx4 v[120:123], v144, s[10:11] offset:2048
	global_load_dwordx4 v[124:127], v144, s[10:11] offset:3072
	global_load_dwordx4 v[128:131], v144, s[12:13] offset:0
	global_load_dwordx4 v[132:135], v144, s[12:13] offset:1024
	global_load_dwordx4 v[136:139], v144, s[12:13] offset:2048
	global_load_dwordx4 v[140:143], v144, s[12:13] offset:3072
	s_and_b32 s42, s28, 7
	s_lshl_b32 s42, s42, 3
	s_bfe_u32 s43, s28, 0x30003
	s_add_i32 s42, s42, s43
	s_lshr_b32 s43, s28, 6
	s_lshl_b32 s42, s42, 8
	s_lshl_b32 s43, s43, 6
	s_add_i32 s42, s42, s43
	s_lshl_b32 s43, s20, 3
	s_add_i32 s23, s42, s43
	s_lshl_b32 s21, s23, 12
	s_add_u32 s40, s8, s21
	s_addc_u32 s41, s9, 0
	s_lshl_b32 s22, s23, 11
	s_add_u32 s42, s30, s22
	s_addc_u32 s43, s31, 0
	s_add_u32 s42, s42, 0x3200000
	s_addc_u32 s43, s43, 0
	s_add_u32 s24, s30, s21
	s_addc_u32 s25, s31, 0
	s_add_u32 s24, s24, 0xabe0000
	s_addc_u32 s25, s25, 0
	s_add_u32 s26, s14, s21
	s_addc_u32 s27, s15, 0
	global_load_dwordx4 v[0:3], v144, s[24:25] offset:0
	global_load_dwordx4 v[4:7], v144, s[24:25] offset:1024
	global_load_dwordx4 v[8:11], v144, s[24:25] offset:2048
	global_load_dwordx4 v[12:15], v144, s[24:25] offset:3072
	global_load_dwordx4 v[16:19], v144, s[26:27] offset:0
	global_load_dwordx4 v[20:23], v144, s[26:27] offset:1024
	global_load_dwordx4 v[24:27], v144, s[26:27] offset:2048
	global_load_dwordx4 v[28:31], v144, s[26:27] offset:3072
	s_add_u32 s24, s24, 0x1000
	s_addc_u32 s25, s25, 0
	s_add_u32 s26, s26, 0x1000
	s_addc_u32 s27, s27, 0
	global_load_dwordx4 v[32:35], v144, s[24:25] offset:0
	global_load_dwordx4 v[36:39], v144, s[24:25] offset:1024
	global_load_dwordx4 v[40:43], v144, s[24:25] offset:2048
	global_load_dwordx4 v[44:47], v144, s[24:25] offset:3072
	global_load_dwordx4 v[48:51], v144, s[26:27] offset:0
	global_load_dwordx4 v[52:55], v144, s[26:27] offset:1024
	global_load_dwordx4 v[56:59], v144, s[26:27] offset:2048
	global_load_dwordx4 v[60:63], v144, s[26:27] offset:3072
	s_add_u32 s24, s24, 0x1000
	s_addc_u32 s25, s25, 0
	s_add_u32 s26, s26, 0x1000
	s_addc_u32 s27, s27, 0
	global_load_dwordx4 v[64:67], v144, s[24:25] offset:0
	global_load_dwordx4 v[68:71], v144, s[24:25] offset:1024
	global_load_dwordx4 v[72:75], v144, s[24:25] offset:2048
	global_load_dwordx4 v[76:79], v144, s[24:25] offset:3072
	global_load_dwordx4 v[80:83], v144, s[26:27] offset:0
	global_load_dwordx4 v[84:87], v144, s[26:27] offset:1024
	global_load_dwordx4 v[88:91], v144, s[26:27] offset:2048
	global_load_dwordx4 v[92:95], v144, s[26:27] offset:3072
	s_add_u32 s24, s24, 0x1000
	s_addc_u32 s25, s25, 0
	s_add_u32 s26, s26, 0x1000
	s_addc_u32 s27, s27, 0
	s_waitcnt vmcnt(16)
	v_mul_f32_e32 v96, v1, v1
	v_mul_f32_e32 v98, v3, v3
	v_fmac_f32_e32 v96, v0, v0
	v_fmac_f32_e32 v98, v2, v2
	v_add_f32_e32 v96, v96, v98
	v_mul_f32_e32 v97, v5, v5
	v_mul_f32_e32 v98, v7, v7
	v_fmac_f32_e32 v97, v4, v4
	v_fmac_f32_e32 v98, v6, v6
	v_add_f32_e32 v97, v97, v98
	v_add_f32_e32 v96, v97, v96
	v_mul_f32_e32 v97, v9, v9
	v_mul_f32_e32 v98, v11, v11
	v_fmac_f32_e32 v97, v8, v8
	v_fmac_f32_e32 v98, v10, v10
	v_add_f32_e32 v97, v97, v98
	v_add_f32_e32 v96, v97, v96
	v_mul_f32_e32 v97, v13, v13
	v_mul_f32_e32 v98, v15, v15
	v_fmac_f32_e32 v97, v12, v12
	v_fmac_f32_e32 v98, v14, v14
	v_add_f32_e32 v97, v97, v98
	v_add_f32_e32 v96, v97, v96
	s_nop 1
	v_add_f32_dpp v96, v96, v96 quad_perm:[1,0,3,2] row_mask:0xf bank_mask:0xf bound_ctrl:1
	s_nop 1
	v_add_f32_dpp v96, v96, v96 quad_perm:[2,3,0,1] row_mask:0xf bank_mask:0xf bound_ctrl:1
	s_nop 1
	v_add_f32_dpp v96, v96, v96 row_half_mirror row_mask:0xf bank_mask:0xf bound_ctrl:1
	s_nop 1
	v_add_f32_dpp v96, v96, v96 row_mirror row_mask:0xf bank_mask:0xf bound_ctrl:1
	v_mov_b32_e32 v97, v96
	s_nop 1
	v_permlane16_swap_b32_e32 v96, v97
	v_add_f32_e32 v96, v96, v97
	v_mov_b32_e32 v97, v96
	s_nop 1
	v_permlane32_swap_b32_e32 v96, v97
	v_add_f32_e32 v96, v96, v97
	v_fmamk_f32 v96, v96, 0x3a800000, v146
	v_mul_f32_e32 v97, 0x4f800000, v96
	v_cmp_gt_f32_e32 vcc, s33, v96
	s_nop 1
	v_cndmask_b32_e32 v96, v96, v97, vcc
	v_sqrt_f32_e32 v97, v96
	s_nop 0
	v_add_u32_e32 v98, -1, v97
	v_fma_f32 v99, -v98, v97, v96
	v_cmp_ge_f32_e64 s[4:5], 0, v99
	v_add_u32_e32 v99, 1, v97
	s_nop 0
	v_cndmask_b32_e64 v98, v97, v98, s[4:5]
	v_fma_f32 v97, -v99, v97, v96
	v_cmp_lt_f32_e64 s[4:5], 0, v97
	s_nop 1
	v_cndmask_b32_e64 v97, v98, v99, s[4:5]
	v_mul_f32_e32 v98, 0x37800000, v97
	v_cndmask_b32_e32 v97, v97, v98, vcc
	v_cmp_class_f32_e32 vcc, v96, v147
	s_nop 1
	v_cndmask_b32_e32 v96, v97, v96, vcc
	v_div_scale_f32 v97, s[4:5], v96, v96, 0.5
	v_rcp_f32_e32 v98, v97
	s_nop 0
	v_fma_f32 v99, -v97, v98, 1.0
	v_fmac_f32_e32 v98, v99, v98
	v_div_scale_f32 v99, vcc, 0.5, v96, 0.5
	v_mul_f32_e32 v100, v99, v98
	v_fma_f32 v101, -v97, v100, v99
; __device__ __forceinline__ unsigned pk2(float lo, float hi) { f32x2 v = {lo, hi}; bf16x2_t b = __builtin_convertvector(v, bf16x2_t); return __builtin_bit_cast(unsigned, b); }
; __device__ __forceinline__ void phase_rowpass(const Ctx& p, const float* F, int base_is_x, float alpha, const float* gpost, const float* gnext, bf16_t* XN, const float* PART, int nsplit) {
;     ...
;         if (more) loadrow(m + NGW, f2, b2);
;         float s = 0.f;
; #pragma unroll
;         for (int j = 0; j < 4; ++j) s += (f[j].x * f[j].x + f[j].y * f[j].y) + (f[j].z * f[j].z + f[j].w * f[j].w);
;         const float rs = alpha / sqrtf(wave_sum_fast(s) * (1.f / DM) + EPS);
;         float s2 = 0.f;
; #pragma unroll
;         for (int j = 0; j < 4; ++j) { b[j] = b[j] + f[j] * rs * gp[j]; s2 += (b[j].x * b[j].x + b[j].y * b[j].y) + (b[j].z * b[j].z + b[j].w * b[j].w);
;             ((f32x4*)(H + (size_t)m * DM))[lane + 64 * j] = b[j]; }
;         if (gnext) {
;             const float r2 = 1.f / sqrtf(wave_sum_fast(s2) * (1.f / DM) + EPS);
;             u32x2* o8 = (u32x2*)(XN + (size_t)m * DM) + lane;
; #pragma unroll
;             for (int j = 0; j < 4; ++j) { u32x2 w; w.x = pk2(b[j].x * r2 * gn[j].x, b[j].y * r2 * gn[j].y); w.y = pk2(b[j].z * r2 * gn[j].z, b[j].w * r2 * gn[j].w); o8[64 * j] = w; }
	v_fmac_f32_e32 v100, v101, v98
	v_fma_f32 v97, -v97, v100, v99
	v_div_fmas_f32 v97, v97, v98, v100
	v_div_fixup_f32 v96, v97, v96, 0.5
	v_mul_f32_e32 v0, v0, v96
	v_mul_f32_e32 v1, v1, v96
	v_mul_f32_e32 v2, v2, v96
	v_mul_f32_e32 v3, v3, v96
	v_mul_f32_e32 v4, v4, v96
	v_mul_f32_e32 v5, v5, v96
	v_mul_f32_e32 v6, v6, v96
	v_mul_f32_e32 v7, v7, v96
	v_mul_f32_e32 v8, v8, v96
	v_mul_f32_e32 v9, v9, v96
	v_mul_f32_e32 v10, v10, v96
	v_mul_f32_e32 v11, v11, v96
	v_mul_f32_e32 v12, v12, v96
	v_mul_f32_e32 v13, v13, v96
	v_mul_f32_e32 v14, v14, v96
	v_mul_f32_e32 v15, v15, v96
	v_fmac_f32_e32 v16, v112, v0
	v_fmac_f32_e32 v17, v113, v1
	v_fmac_f32_e32 v18, v114, v2
	v_fmac_f32_e32 v19, v115, v3
	v_fmac_f32_e32 v20, v116, v4
	v_fmac_f32_e32 v21, v117, v5
	v_fmac_f32_e32 v22, v118, v6
	v_fmac_f32_e32 v23, v119, v7
	v_fmac_f32_e32 v24, v120, v8
	v_fmac_f32_e32 v25, v121, v9
	v_fmac_f32_e32 v26, v122, v10
	v_fmac_f32_e32 v27, v123, v11
	v_fmac_f32_e32 v28, v124, v12
	v_fmac_f32_e32 v29, v125, v13
	v_fmac_f32_e32 v30, v126, v14
	v_fmac_f32_e32 v31, v127, v15
	global_store_dwordx4 v144, v[16:19], s[40:41] offset:0
	global_store_dwordx4 v144, v[20:23], s[40:41] offset:1024
	global_store_dwordx4 v144, v[24:27], s[40:41] offset:2048
	global_store_dwordx4 v144, v[28:31], s[40:41] offset:3072
	v_mul_f32_e32 v96, v17, v17
	v_mul_f32_e32 v98, v19, v19
	v_fmac_f32_e32 v96, v16, v16
	v_fmac_f32_e32 v98, v18, v18
	v_add_f32_e32 v96, v96, v98
	v_mul_f32_e32 v97, v21, v21
	v_mul_f32_e32 v98, v23, v23
	v_fmac_f32_e32 v97, v20, v20
	v_fmac_f32_e32 v98, v22, v22
	v_add_f32_e32 v97, v97, v98
	v_add_f32_e32 v96, v97, v96
	v_mul_f32_e32 v97, v25, v25
	v_mul_f32_e32 v98, v27, v27
	v_fmac_f32_e32 v97, v24, v24
	v_fmac_f32_e32 v98, v26, v26
	v_add_f32_e32 v97, v97, v98
	v_add_f32_e32 v96, v97, v96
	v_mul_f32_e32 v97, v29, v29
	v_mul_f32_e32 v98, v31, v31
	v_fmac_f32_e32 v97, v28, v28
	v_fmac_f32_e32 v98, v30, v30
	v_add_f32_e32 v97, v97, v98
	v_add_f32_e32 v96, v97, v96
	s_nop 1
	v_add_f32_dpp v96, v96, v96 quad_perm:[1,0,3,2] row_mask:0xf bank_mask:0xf bound_ctrl:1
	s_nop 1
	v_add_f32_dpp v96, v96, v96 quad_perm:[2,3,0,1] row_mask:0xf bank_mask:0xf bound_ctrl:1
	s_nop 1
	v_add_f32_dpp v96, v96, v96 row_half_mirror row_mask:0xf bank_mask:0xf bound_ctrl:1
	s_nop 1
	v_add_f32_dpp v96, v96, v96 row_mirror row_mask:0xf bank_mask:0xf bound_ctrl:1
	v_mov_b32_e32 v97, v96
	s_nop 1
	v_permlane16_swap_b32_e32 v96, v97
	v_add_f32_e32 v96, v96, v97
	v_mov_b32_e32 v97, v96
	s_nop 1
	v_permlane32_swap_b32_e32 v96, v97
	v_add_f32_e32 v96, v96, v97
	v_fmamk_f32 v96, v96, 0x3a800000, v146
	v_mul_f32_e32 v97, 0x4f800000, v96
	v_cmp_gt_f32_e32 vcc, s33, v96
	s_nop 1
	v_cndmask_b32_e32 v96, v96, v97, vcc
	v_sqrt_f32_e32 v97, v96
	s_nop 0
	v_add_u32_e32 v98, -1, v97
	v_fma_f32 v99, -v98, v97, v96
	v_cmp_ge_f32_e64 s[4:5], 0, v99
	v_add_u32_e32 v99, 1, v97
	s_nop 0
	v_cndmask_b32_e64 v98, v97, v98, s[4:5]
	v_fma_f32 v97, -v99, v97, v96
	v_cmp_lt_f32_e64 s[4:5], 0, v97
	s_nop 1
	v_cndmask_b32_e64 v97, v98, v99, s[4:5]
	v_mul_f32_e32 v98, 0x37800000, v97
	v_cndmask_b32_e32 v97, v97, v98, vcc
	v_cmp_class_f32_e32 vcc, v96, v147
	s_nop 1
	v_cndmask_b32_e32 v96, v97, v96, vcc
	v_div_scale_f32 v97, s[4:5], v96, v96, 1.0
	v_rcp_f32_e32 v98, v97
	s_nop 0
	v_fma_f32 v99, -v97, v98, 1.0
	v_fmac_f32_e32 v98, v99, v98
	v_div_scale_f32 v99, vcc, 1.0, v96, 1.0
	v_mul_f32_e32 v100, v99, v98
	v_fma_f32 v101, -v97, v100, v99
	v_fmac_f32_e32 v100, v101, v98
	v_fma_f32 v97, -v97, v100, v99
	v_div_fmas_f32 v97, v97, v98, v100
	v_div_fixup_f32 v96, v97, v96, 1.0
	v_mul_f32_e32 v0, v16, v96
	v_mul_f32_e32 v1, v17, v96
	v_mul_f32_e32 v2, v18, v96
	v_mul_f32_e32 v3, v19, v96
	v_mul_f32_e32 v4, v20, v96
	v_mul_f32_e32 v5, v21, v96
	v_mul_f32_e32 v6, v22, v96
	v_mul_f32_e32 v7, v23, v96
	v_mul_f32_e32 v8, v24, v96
	v_mul_f32_e32 v9, v25, v96
	v_mul_f32_e32 v10, v26, v96
	v_mul_f32_e32 v11, v27, v96
	v_mul_f32_e32 v12, v28, v96
	v_mul_f32_e32 v13, v29, v96
	v_mul_f32_e32 v14, v30, v96
	v_mul_f32_e32 v15, v31, v96
	v_mul_f32_e32 v0, v128, v0
	v_mul_f32_e32 v1, v129, v1
	v_mul_f32_e32 v2, v130, v2
	v_mul_f32_e32 v3, v131, v3
	v_mul_f32_e32 v4, v132, v4
	v_mul_f32_e32 v5, v133, v5
	v_mul_f32_e32 v6, v134, v6
	v_mul_f32_e32 v7, v135, v7
	v_mul_f32_e32 v8, v136, v8
	v_mul_f32_e32 v9, v137, v9
	v_mul_f32_e32 v10, v138, v10
	v_mul_f32_e32 v11, v139, v11
	v_mul_f32_e32 v12, v140, v12
	v_mul_f32_e32 v13, v141, v13
	v_mul_f32_e32 v14, v142, v14
	v_mul_f32_e32 v15, v143, v15
	v_cvt_pk_bf16_f32 v148, v0, v1
	v_cvt_pk_bf16_f32 v149, v2, v3
	global_store_dwordx2 v145, v[148:149], s[42:43] offset:0
	v_cvt_pk_bf16_f32 v150, v4, v5
	v_cvt_pk_bf16_f32 v151, v6, v7
	global_store_dwordx2 v145, v[150:151], s[42:43] offset:512
	v_cvt_pk_bf16_f32 v152, v8, v9
	v_cvt_pk_bf16_f32 v153, v10, v11
	global_store_dwordx2 v145, v[152:153], s[42:43] offset:1024
	v_cvt_pk_bf16_f32 v154, v12, v13
	v_cvt_pk_bf16_f32 v155, v14, v15
	global_store_dwordx2 v145, v[154:155], s[42:43] offset:1536
	s_add_u32 s40, s40, 0x1000
	s_addc_u32 s41, s41, 0
	s_add_u32 s42, s42, 0x800
	s_addc_u32 s43, s43, 0
	global_load_dwordx4 v[0:3], v144, s[24:25] offset:0
	global_load_dwordx4 v[4:7], v144, s[24:25] offset:1024
	global_load_dwordx4 v[8:11], v144, s[24:25] offset:2048
	global_load_dwordx4 v[12:15], v144, s[24:25] offset:3072
	global_load_dwordx4 v[16:19], v144, s[26:27] offset:0
	global_load_dwordx4 v[20:23], v144, s[26:27] offset:1024
	global_load_dwordx4 v[24:27], v144, s[26:27] offset:2048
	global_load_dwordx4 v[28:31], v144, s[26:27] offset:3072
	s_add_u32 s24, s24, 0x1000
	s_addc_u32 s25, s25, 0
	s_add_u32 s26, s26, 0x1000
	s_addc_u32 s27, s27, 0
	s_waitcnt vmcnt(24)
; __device__ __forceinline__ void phase_rowpass(const Ctx& p, const float* F, int base_is_x, float alpha, const float* gpost, const float* gnext, bf16_t* XN, const float* PART, int nsplit) {
;     ...
;         float s = 0.f;
; #pragma unroll
;         for (int j = 0; j < 4; ++j) s += (f[j].x * f[j].x + f[j].y * f[j].y) + (f[j].z * f[j].z + f[j].w * f[j].w);
;         const float rs = alpha / sqrtf(wave_sum_fast(s) * (1.f / DM) + EPS);
;         float s2 = 0.f;
; #pragma unroll
;         for (int j = 0; j < 4; ++j) { b[j] = b[j] + f[j] * rs * gp[j]; s2 += (b[j].x * b[j].x + b[j].y * b[j].y) + (b[j].z * b[j].z + b[j].w * b[j].w);
;             ((f32x4*)(H + (size_t)m * DM))[lane + 64 * j] = b[j]; }
;         if (gnext) {
;             const float r2 = 1.f / sqrtf(wave_sum_fast(s2) * (1.f / DM) + EPS);
	v_mul_f32_e32 v96, v33, v33
	v_mul_f32_e32 v98, v35, v35
	v_fmac_f32_e32 v96, v32, v32
	v_fmac_f32_e32 v98, v34, v34
	v_add_f32_e32 v96, v96, v98
	v_mul_f32_e32 v97, v37, v37
	v_mul_f32_e32 v98, v39, v39
	v_fmac_f32_e32 v97, v36, v36
	v_fmac_f32_e32 v98, v38, v38
	v_add_f32_e32 v97, v97, v98
	v_add_f32_e32 v96, v97, v96
	v_mul_f32_e32 v97, v41, v41
	v_mul_f32_e32 v98, v43, v43
	v_fmac_f32_e32 v97, v40, v40
	v_fmac_f32_e32 v98, v42, v42
	v_add_f32_e32 v97, v97, v98
	v_add_f32_e32 v96, v97, v96
	v_mul_f32_e32 v97, v45, v45
	v_mul_f32_e32 v98, v47, v47
	v_fmac_f32_e32 v97, v44, v44
	v_fmac_f32_e32 v98, v46, v46
	v_add_f32_e32 v97, v97, v98
	v_add_f32_e32 v96, v97, v96
	s_nop 1
	v_add_f32_dpp v96, v96, v96 quad_perm:[1,0,3,2] row_mask:0xf bank_mask:0xf bound_ctrl:1
	s_nop 1
	v_add_f32_dpp v96, v96, v96 quad_perm:[2,3,0,1] row_mask:0xf bank_mask:0xf bound_ctrl:1
	s_nop 1
	v_add_f32_dpp v96, v96, v96 row_half_mirror row_mask:0xf bank_mask:0xf bound_ctrl:1
	s_nop 1
	v_add_f32_dpp v96, v96, v96 row_mirror row_mask:0xf bank_mask:0xf bound_ctrl:1
	v_mov_b32_e32 v97, v96
	s_nop 1
	v_permlane16_swap_b32_e32 v96, v97
	v_add_f32_e32 v96, v96, v97
	v_mov_b32_e32 v97, v96
	s_nop 1
	v_permlane32_swap_b32_e32 v96, v97
	v_add_f32_e32 v96, v96, v97
	v_fmamk_f32 v96, v96, 0x3a800000, v146
	v_mul_f32_e32 v97, 0x4f800000, v96
	v_cmp_gt_f32_e32 vcc, s33, v96
	s_nop 1
	v_cndmask_b32_e32 v96, v96, v97, vcc
	v_sqrt_f32_e32 v97, v96
	s_nop 0
	v_add_u32_e32 v98, -1, v97
	v_fma_f32 v99, -v98, v97, v96
	v_cmp_ge_f32_e64 s[4:5], 0, v99
	v_add_u32_e32 v99, 1, v97
	s_nop 0
	v_cndmask_b32_e64 v98, v97, v98, s[4:5]
	v_fma_f32 v97, -v99, v97, v96
	v_cmp_lt_f32_e64 s[4:5], 0, v97
	s_nop 1
	v_cndmask_b32_e64 v97, v98, v99, s[4:5]
	v_mul_f32_e32 v98, 0x37800000, v97
	v_cndmask_b32_e32 v97, v97, v98, vcc
	v_cmp_class_f32_e32 vcc, v96, v147
	s_nop 1
	v_cndmask_b32_e32 v96, v97, v96, vcc
	v_div_scale_f32 v97, s[4:5], v96, v96, 0.5
	v_rcp_f32_e32 v98, v97
	s_nop 0
	v_fma_f32 v99, -v97, v98, 1.0
	v_fmac_f32_e32 v98, v99, v98
	v_div_scale_f32 v99, vcc, 0.5, v96, 0.5
	v_mul_f32_e32 v100, v99, v98
	v_fma_f32 v101, -v97, v100, v99
	v_fmac_f32_e32 v100, v101, v98
	v_fma_f32 v97, -v97, v100, v99
	v_div_fmas_f32 v97, v97, v98, v100
	v_div_fixup_f32 v96, v97, v96, 0.5
	v_mul_f32_e32 v32, v32, v96
	v_mul_f32_e32 v33, v33, v96
	v_mul_f32_e32 v34, v34, v96
	v_mul_f32_e32 v35, v35, v96
	v_mul_f32_e32 v36, v36, v96
	v_mul_f32_e32 v37, v37, v96
	v_mul_f32_e32 v38, v38, v96
	v_mul_f32_e32 v39, v39, v96
	v_mul_f32_e32 v40, v40, v96
	v_mul_f32_e32 v41, v41, v96
	v_mul_f32_e32 v42, v42, v96
	v_mul_f32_e32 v43, v43, v96
	v_mul_f32_e32 v44, v44, v96
	v_mul_f32_e32 v45, v45, v96
	v_mul_f32_e32 v46, v46, v96
	v_mul_f32_e32 v47, v47, v96
	v_fmac_f32_e32 v48, v112, v32
	v_fmac_f32_e32 v49, v113, v33
	v_fmac_f32_e32 v50, v114, v34
	v_fmac_f32_e32 v51, v115, v35
	v_fmac_f32_e32 v52, v116, v36
	v_fmac_f32_e32 v53, v117, v37
	v_fmac_f32_e32 v54, v118, v38
	v_fmac_f32_e32 v55, v119, v39
	v_fmac_f32_e32 v56, v120, v40
	v_fmac_f32_e32 v57, v121, v41
	v_fmac_f32_e32 v58, v122, v42
	v_fmac_f32_e32 v59, v123, v43
	v_fmac_f32_e32 v60, v124, v44
	v_fmac_f32_e32 v61, v125, v45
	v_fmac_f32_e32 v62, v126, v46
	v_fmac_f32_e32 v63, v127, v47
	global_store_dwordx4 v144, v[48:51], s[40:41] offset:0
	global_store_dwordx4 v144, v[52:55], s[40:41] offset:1024
	global_store_dwordx4 v144, v[56:59], s[40:41] offset:2048
	global_store_dwordx4 v144, v[60:63], s[40:41] offset:3072
	v_mul_f32_e32 v96, v49, v49
	v_mul_f32_e32 v98, v51, v51
	v_fmac_f32_e32 v96, v48, v48
	v_fmac_f32_e32 v98, v50, v50
	v_add_f32_e32 v96, v96, v98
	v_mul_f32_e32 v97, v53, v53
	v_mul_f32_e32 v98, v55, v55
	v_fmac_f32_e32 v97, v52, v52
	v_fmac_f32_e32 v98, v54, v54
	v_add_f32_e32 v97, v97, v98
	v_add_f32_e32 v96, v97, v96
	v_mul_f32_e32 v97, v57, v57
	v_mul_f32_e32 v98, v59, v59
	v_fmac_f32_e32 v97, v56, v56
	v_fmac_f32_e32 v98, v58, v58
	v_add_f32_e32 v97, v97, v98
	v_add_f32_e32 v96, v97, v96
	v_mul_f32_e32 v97, v61, v61
	v_mul_f32_e32 v98, v63, v63
	v_fmac_f32_e32 v97, v60, v60
	v_fmac_f32_e32 v98, v62, v62
	v_add_f32_e32 v97, v97, v98
	v_add_f32_e32 v96, v97, v96
	s_nop 1
	v_add_f32_dpp v96, v96, v96 quad_perm:[1,0,3,2] row_mask:0xf bank_mask:0xf bound_ctrl:1
	s_nop 1
	v_add_f32_dpp v96, v96, v96 quad_perm:[2,3,0,1] row_mask:0xf bank_mask:0xf bound_ctrl:1
	s_nop 1
	v_add_f32_dpp v96, v96, v96 row_half_mirror row_mask:0xf bank_mask:0xf bound_ctrl:1
	s_nop 1
	v_add_f32_dpp v96, v96, v96 row_mirror row_mask:0xf bank_mask:0xf bound_ctrl:1
	v_mov_b32_e32 v97, v96
	s_nop 1
	v_permlane16_swap_b32_e32 v96, v97
	v_add_f32_e32 v96, v96, v97
	v_mov_b32_e32 v97, v96
	s_nop 1
	v_permlane32_swap_b32_e32 v96, v97
	v_add_f32_e32 v96, v96, v97
	v_fmamk_f32 v96, v96, 0x3a800000, v146
	v_mul_f32_e32 v97, 0x4f800000, v96
	v_cmp_gt_f32_e32 vcc, s33, v96
	s_nop 1
	v_cndmask_b32_e32 v96, v96, v97, vcc
	v_sqrt_f32_e32 v97, v96
	s_nop 0
	v_add_u32_e32 v98, -1, v97
	v_fma_f32 v99, -v98, v97, v96
	v_cmp_ge_f32_e64 s[4:5], 0, v99
	v_add_u32_e32 v99, 1, v97
	s_nop 0
	v_cndmask_b32_e64 v98, v97, v98, s[4:5]
	v_fma_f32 v97, -v99, v97, v96
	v_cmp_lt_f32_e64 s[4:5], 0, v97
	s_nop 1
	v_cndmask_b32_e64 v97, v98, v99, s[4:5]
	v_mul_f32_e32 v98, 0x37800000, v97
	v_cndmask_b32_e32 v97, v97, v98, vcc
	v_cmp_class_f32_e32 vcc, v96, v147
	s_nop 1
	v_cndmask_b32_e32 v96, v97, v96, vcc
	v_div_scale_f32 v97, s[4:5], v96, v96, 1.0
	v_rcp_f32_e32 v98, v97
	s_nop 0
	v_fma_f32 v99, -v97, v98, 1.0
	v_fmac_f32_e32 v98, v99, v98
	v_div_scale_f32 v99, vcc, 1.0, v96, 1.0
	v_mul_f32_e32 v100, v99, v98
	v_fma_f32 v101, -v97, v100, v99
	v_fmac_f32_e32 v100, v101, v98
	v_fma_f32 v97, -v97, v100, v99
; __device__ __forceinline__ unsigned pk2(float lo, float hi) { f32x2 v = {lo, hi}; bf16x2_t b = __builtin_convertvector(v, bf16x2_t); return __builtin_bit_cast(unsigned, b); }
; __device__ __forceinline__ void phase_rowpass(const Ctx& p, const float* F, int base_is_x, float alpha, const float* gpost, const float* gnext, bf16_t* XN, const float* PART, int nsplit) {
;     ...
;         if (more) loadrow(m + NGW, f2, b2);
;         float s = 0.f;
; #pragma unroll
;         for (int j = 0; j < 4; ++j) s += (f[j].x * f[j].x + f[j].y * f[j].y) + (f[j].z * f[j].z + f[j].w * f[j].w);
;         const float rs = alpha / sqrtf(wave_sum_fast(s) * (1.f / DM) + EPS);
;         float s2 = 0.f;
; #pragma unroll
;         for (int j = 0; j < 4; ++j) { b[j] = b[j] + f[j] * rs * gp[j]; s2 += (b[j].x * b[j].x + b[j].y * b[j].y) + (b[j].z * b[j].z + b[j].w * b[j].w);
;             ((f32x4*)(H + (size_t)m * DM))[lane + 64 * j] = b[j]; }
;     ...
;             u32x2* o8 = (u32x2*)(XN + (size_t)m * DM) + lane;
; #pragma unroll
;             for (int j = 0; j < 4; ++j) { u32x2 w; w.x = pk2(b[j].x * r2 * gn[j].x, b[j].y * r2 * gn[j].y); w.y = pk2(b[j].z * r2 * gn[j].z, b[j].w * r2 * gn[j].w); o8[64 * j] = w; }
	v_div_fmas_f32 v97, v97, v98, v100
	v_div_fixup_f32 v96, v97, v96, 1.0
	v_mul_f32_e32 v32, v48, v96
	v_mul_f32_e32 v33, v49, v96
	v_mul_f32_e32 v34, v50, v96
	v_mul_f32_e32 v35, v51, v96
	v_mul_f32_e32 v36, v52, v96
	v_mul_f32_e32 v37, v53, v96
	v_mul_f32_e32 v38, v54, v96
	v_mul_f32_e32 v39, v55, v96
	v_mul_f32_e32 v40, v56, v96
	v_mul_f32_e32 v41, v57, v96
	v_mul_f32_e32 v42, v58, v96
	v_mul_f32_e32 v43, v59, v96
	v_mul_f32_e32 v44, v60, v96
	v_mul_f32_e32 v45, v61, v96
	v_mul_f32_e32 v46, v62, v96
	v_mul_f32_e32 v47, v63, v96
	v_mul_f32_e32 v32, v128, v32
	v_mul_f32_e32 v33, v129, v33
	v_mul_f32_e32 v34, v130, v34
	v_mul_f32_e32 v35, v131, v35
	v_mul_f32_e32 v36, v132, v36
	v_mul_f32_e32 v37, v133, v37
	v_mul_f32_e32 v38, v134, v38
	v_mul_f32_e32 v39, v135, v39
	v_mul_f32_e32 v40, v136, v40
	v_mul_f32_e32 v41, v137, v41
	v_mul_f32_e32 v42, v138, v42
	v_mul_f32_e32 v43, v139, v43
	v_mul_f32_e32 v44, v140, v44
	v_mul_f32_e32 v45, v141, v45
	v_mul_f32_e32 v46, v142, v46
	v_mul_f32_e32 v47, v143, v47
	v_cvt_pk_bf16_f32 v148, v32, v33
	v_cvt_pk_bf16_f32 v149, v34, v35
	global_store_dwordx2 v145, v[148:149], s[42:43] offset:0
	v_cvt_pk_bf16_f32 v150, v36, v37
	v_cvt_pk_bf16_f32 v151, v38, v39
	global_store_dwordx2 v145, v[150:151], s[42:43] offset:512
	v_cvt_pk_bf16_f32 v152, v40, v41
	v_cvt_pk_bf16_f32 v153, v42, v43
	global_store_dwordx2 v145, v[152:153], s[42:43] offset:1024
	v_cvt_pk_bf16_f32 v154, v44, v45
	v_cvt_pk_bf16_f32 v155, v46, v47
	global_store_dwordx2 v145, v[154:155], s[42:43] offset:1536
	s_add_u32 s40, s40, 0x1000
	s_addc_u32 s41, s41, 0
	s_add_u32 s42, s42, 0x800
	s_addc_u32 s43, s43, 0
	global_load_dwordx4 v[32:35], v144, s[24:25] offset:0
	global_load_dwordx4 v[36:39], v144, s[24:25] offset:1024
	global_load_dwordx4 v[40:43], v144, s[24:25] offset:2048
	global_load_dwordx4 v[44:47], v144, s[24:25] offset:3072
	global_load_dwordx4 v[48:51], v144, s[26:27] offset:0
	global_load_dwordx4 v[52:55], v144, s[26:27] offset:1024
	global_load_dwordx4 v[56:59], v144, s[26:27] offset:2048
	global_load_dwordx4 v[60:63], v144, s[26:27] offset:3072
	s_add_u32 s24, s24, 0x1000
	s_addc_u32 s25, s25, 0
	s_add_u32 s26, s26, 0x1000
	s_addc_u32 s27, s27, 0
	s_waitcnt vmcnt(32)
	v_mul_f32_e32 v96, v65, v65
	v_mul_f32_e32 v98, v67, v67
	v_fmac_f32_e32 v96, v64, v64
	v_fmac_f32_e32 v98, v66, v66
	v_add_f32_e32 v96, v96, v98
	v_mul_f32_e32 v97, v69, v69
	v_mul_f32_e32 v98, v71, v71
	v_fmac_f32_e32 v97, v68, v68
	v_fmac_f32_e32 v98, v70, v70
	v_add_f32_e32 v97, v97, v98
	v_add_f32_e32 v96, v97, v96
	v_mul_f32_e32 v97, v73, v73
	v_mul_f32_e32 v98, v75, v75
	v_fmac_f32_e32 v97, v72, v72
	v_fmac_f32_e32 v98, v74, v74
	v_add_f32_e32 v97, v97, v98
	v_add_f32_e32 v96, v97, v96
	v_mul_f32_e32 v97, v77, v77
	v_mul_f32_e32 v98, v79, v79
	v_fmac_f32_e32 v97, v76, v76
	v_fmac_f32_e32 v98, v78, v78
	v_add_f32_e32 v97, v97, v98
	v_add_f32_e32 v96, v97, v96
	s_nop 1
	v_add_f32_dpp v96, v96, v96 quad_perm:[1,0,3,2] row_mask:0xf bank_mask:0xf bound_ctrl:1
	s_nop 1
	v_add_f32_dpp v96, v96, v96 quad_perm:[2,3,0,1] row_mask:0xf bank_mask:0xf bound_ctrl:1
	s_nop 1
	v_add_f32_dpp v96, v96, v96 row_half_mirror row_mask:0xf bank_mask:0xf bound_ctrl:1
	s_nop 1
	v_add_f32_dpp v96, v96, v96 row_mirror row_mask:0xf bank_mask:0xf bound_ctrl:1
	v_mov_b32_e32 v97, v96
	s_nop 1
	v_permlane16_swap_b32_e32 v96, v97
	v_add_f32_e32 v96, v96, v97
	v_mov_b32_e32 v97, v96
	s_nop 1
	v_permlane32_swap_b32_e32 v96, v97
	v_add_f32_e32 v96, v96, v97
	v_fmamk_f32 v96, v96, 0x3a800000, v146
	v_mul_f32_e32 v97, 0x4f800000, v96
	v_cmp_gt_f32_e32 vcc, s33, v96
	s_nop 1
	v_cndmask_b32_e32 v96, v96, v97, vcc
	v_sqrt_f32_e32 v97, v96
	s_nop 0
	v_add_u32_e32 v98, -1, v97
	v_fma_f32 v99, -v98, v97, v96
	v_cmp_ge_f32_e64 s[4:5], 0, v99
	v_add_u32_e32 v99, 1, v97
	s_nop 0
	v_cndmask_b32_e64 v98, v97, v98, s[4:5]
	v_fma_f32 v97, -v99, v97, v96
	v_cmp_lt_f32_e64 s[4:5], 0, v97
	s_nop 1
	v_cndmask_b32_e64 v97, v98, v99, s[4:5]
	v_mul_f32_e32 v98, 0x37800000, v97
	v_cndmask_b32_e32 v97, v97, v98, vcc
	v_cmp_class_f32_e32 vcc, v96, v147
	s_nop 1
	v_cndmask_b32_e32 v96, v97, v96, vcc
	v_div_scale_f32 v97, s[4:5], v96, v96, 0.5
	v_rcp_f32_e32 v98, v97
	s_nop 0
	v_fma_f32 v99, -v97, v98, 1.0
	v_fmac_f32_e32 v98, v99, v98
	v_div_scale_f32 v99, vcc, 0.5, v96, 0.5
	v_mul_f32_e32 v100, v99, v98
	v_fma_f32 v101, -v97, v100, v99
	v_fmac_f32_e32 v100, v101, v98
	v_fma_f32 v97, -v97, v100, v99
	v_div_fmas_f32 v97, v97, v98, v100
	v_div_fixup_f32 v96, v97, v96, 0.5
	v_mul_f32_e32 v64, v64, v96
	v_mul_f32_e32 v65, v65, v96
	v_mul_f32_e32 v66, v66, v96
	v_mul_f32_e32 v67, v67, v96
	v_mul_f32_e32 v68, v68, v96
	v_mul_f32_e32 v69, v69, v96
	v_mul_f32_e32 v70, v70, v96
	v_mul_f32_e32 v71, v71, v96
	v_mul_f32_e32 v72, v72, v96
	v_mul_f32_e32 v73, v73, v96
	v_mul_f32_e32 v74, v74, v96
	v_mul_f32_e32 v75, v75, v96
	v_mul_f32_e32 v76, v76, v96
	v_mul_f32_e32 v77, v77, v96
	v_mul_f32_e32 v78, v78, v96
	v_mul_f32_e32 v79, v79, v96
	v_fmac_f32_e32 v80, v112, v64
	v_fmac_f32_e32 v81, v113, v65
	v_fmac_f32_e32 v82, v114, v66
	v_fmac_f32_e32 v83, v115, v67
	v_fmac_f32_e32 v84, v116, v68
	v_fmac_f32_e32 v85, v117, v69
	v_fmac_f32_e32 v86, v118, v70
	v_fmac_f32_e32 v87, v119, v71
	v_fmac_f32_e32 v88, v120, v72
	v_fmac_f32_e32 v89, v121, v73
	v_fmac_f32_e32 v90, v122, v74
	v_fmac_f32_e32 v91, v123, v75
	v_fmac_f32_e32 v92, v124, v76
	v_fmac_f32_e32 v93, v125, v77
	v_fmac_f32_e32 v94, v126, v78
	v_fmac_f32_e32 v95, v127, v79
	global_store_dwordx4 v144, v[80:83], s[40:41] offset:0
	global_store_dwordx4 v144, v[84:87], s[40:41] offset:1024
	global_store_dwordx4 v144, v[88:91], s[40:41] offset:2048
	global_store_dwordx4 v144, v[92:95], s[40:41] offset:3072
; __device__ __forceinline__ unsigned pk2(float lo, float hi) { f32x2 v = {lo, hi}; bf16x2_t b = __builtin_convertvector(v, bf16x2_t); return __builtin_bit_cast(unsigned, b); }
; __device__ __forceinline__ void phase_rowpass(const Ctx& p, const float* F, int base_is_x, float alpha, const float* gpost, const float* gnext, bf16_t* XN, const float* PART, int nsplit) {
;     ...
;         if (more) loadrow(m + NGW, f2, b2);
;     ...
;             const float r2 = 1.f / sqrtf(wave_sum_fast(s2) * (1.f / DM) + EPS);
;             u32x2* o8 = (u32x2*)(XN + (size_t)m * DM) + lane;
; #pragma unroll
;             for (int j = 0; j < 4; ++j) { u32x2 w; w.x = pk2(b[j].x * r2 * gn[j].x, b[j].y * r2 * gn[j].y); w.y = pk2(b[j].z * r2 * gn[j].z, b[j].w * r2 * gn[j].w); o8[64 * j] = w; }
	v_mul_f32_e32 v96, v81, v81
	v_mul_f32_e32 v98, v83, v83
	v_fmac_f32_e32 v96, v80, v80
	v_fmac_f32_e32 v98, v82, v82
	v_add_f32_e32 v96, v96, v98
	v_mul_f32_e32 v97, v85, v85
	v_mul_f32_e32 v98, v87, v87
	v_fmac_f32_e32 v97, v84, v84
	v_fmac_f32_e32 v98, v86, v86
	v_add_f32_e32 v97, v97, v98
	v_add_f32_e32 v96, v97, v96
	v_mul_f32_e32 v97, v89, v89
	v_mul_f32_e32 v98, v91, v91
	v_fmac_f32_e32 v97, v88, v88
	v_fmac_f32_e32 v98, v90, v90
	v_add_f32_e32 v97, v97, v98
	v_add_f32_e32 v96, v97, v96
	v_mul_f32_e32 v97, v93, v93
	v_mul_f32_e32 v98, v95, v95
	v_fmac_f32_e32 v97, v92, v92
	v_fmac_f32_e32 v98, v94, v94
	v_add_f32_e32 v97, v97, v98
	v_add_f32_e32 v96, v97, v96
	s_nop 1
	v_add_f32_dpp v96, v96, v96 quad_perm:[1,0,3,2] row_mask:0xf bank_mask:0xf bound_ctrl:1
	s_nop 1
	v_add_f32_dpp v96, v96, v96 quad_perm:[2,3,0,1] row_mask:0xf bank_mask:0xf bound_ctrl:1
	s_nop 1
	v_add_f32_dpp v96, v96, v96 row_half_mirror row_mask:0xf bank_mask:0xf bound_ctrl:1
	s_nop 1
	v_add_f32_dpp v96, v96, v96 row_mirror row_mask:0xf bank_mask:0xf bound_ctrl:1
	v_mov_b32_e32 v97, v96
	s_nop 1
	v_permlane16_swap_b32_e32 v96, v97
	v_add_f32_e32 v96, v96, v97
	v_mov_b32_e32 v97, v96
	s_nop 1
	v_permlane32_swap_b32_e32 v96, v97
	v_add_f32_e32 v96, v96, v97
	v_fmamk_f32 v96, v96, 0x3a800000, v146
	v_mul_f32_e32 v97, 0x4f800000, v96
	v_cmp_gt_f32_e32 vcc, s33, v96
	s_nop 1
	v_cndmask_b32_e32 v96, v96, v97, vcc
	v_sqrt_f32_e32 v97, v96
	s_nop 0
	v_add_u32_e32 v98, -1, v97
	v_fma_f32 v99, -v98, v97, v96
	v_cmp_ge_f32_e64 s[4:5], 0, v99
	v_add_u32_e32 v99, 1, v97
	s_nop 0
	v_cndmask_b32_e64 v98, v97, v98, s[4:5]
	v_fma_f32 v97, -v99, v97, v96
	v_cmp_lt_f32_e64 s[4:5], 0, v97
	s_nop 1
	v_cndmask_b32_e64 v97, v98, v99, s[4:5]
	v_mul_f32_e32 v98, 0x37800000, v97
	v_cndmask_b32_e32 v97, v97, v98, vcc
	v_cmp_class_f32_e32 vcc, v96, v147
	s_nop 1
	v_cndmask_b32_e32 v96, v97, v96, vcc
	v_div_scale_f32 v97, s[4:5], v96, v96, 1.0
	v_rcp_f32_e32 v98, v97
	s_nop 0
	v_fma_f32 v99, -v97, v98, 1.0
	v_fmac_f32_e32 v98, v99, v98
	v_div_scale_f32 v99, vcc, 1.0, v96, 1.0
	v_mul_f32_e32 v100, v99, v98
	v_fma_f32 v101, -v97, v100, v99
	v_fmac_f32_e32 v100, v101, v98
	v_fma_f32 v97, -v97, v100, v99
	v_div_fmas_f32 v97, v97, v98, v100
	v_div_fixup_f32 v96, v97, v96, 1.0
	v_mul_f32_e32 v64, v80, v96
	v_mul_f32_e32 v65, v81, v96
	v_mul_f32_e32 v66, v82, v96
	v_mul_f32_e32 v67, v83, v96
	v_mul_f32_e32 v68, v84, v96
	v_mul_f32_e32 v69, v85, v96
	v_mul_f32_e32 v70, v86, v96
	v_mul_f32_e32 v71, v87, v96
	v_mul_f32_e32 v72, v88, v96
	v_mul_f32_e32 v73, v89, v96
	v_mul_f32_e32 v74, v90, v96
	v_mul_f32_e32 v75, v91, v96
	v_mul_f32_e32 v76, v92, v96
	v_mul_f32_e32 v77, v93, v96
	v_mul_f32_e32 v78, v94, v96
	v_mul_f32_e32 v79, v95, v96
	v_mul_f32_e32 v64, v128, v64
	v_mul_f32_e32 v65, v129, v65
	v_mul_f32_e32 v66, v130, v66
	v_mul_f32_e32 v67, v131, v67
	v_mul_f32_e32 v68, v132, v68
	v_mul_f32_e32 v69, v133, v69
	v_mul_f32_e32 v70, v134, v70
	v_mul_f32_e32 v71, v135, v71
	v_mul_f32_e32 v72, v136, v72
	v_mul_f32_e32 v73, v137, v73
	v_mul_f32_e32 v74, v138, v74
	v_mul_f32_e32 v75, v139, v75
	v_mul_f32_e32 v76, v140, v76
	v_mul_f32_e32 v77, v141, v77
	v_mul_f32_e32 v78, v142, v78
	v_mul_f32_e32 v79, v143, v79
	v_cvt_pk_bf16_f32 v148, v64, v65
	v_cvt_pk_bf16_f32 v149, v66, v67
	global_store_dwordx2 v145, v[148:149], s[42:43] offset:0
	v_cvt_pk_bf16_f32 v150, v68, v69
	v_cvt_pk_bf16_f32 v151, v70, v71
	global_store_dwordx2 v145, v[150:151], s[42:43] offset:512
	v_cvt_pk_bf16_f32 v152, v72, v73
	v_cvt_pk_bf16_f32 v153, v74, v75
	global_store_dwordx2 v145, v[152:153], s[42:43] offset:1024
	v_cvt_pk_bf16_f32 v154, v76, v77
	v_cvt_pk_bf16_f32 v155, v78, v79
	global_store_dwordx2 v145, v[154:155], s[42:43] offset:1536
	s_add_u32 s40, s40, 0x1000
	s_addc_u32 s41, s41, 0
	s_add_u32 s42, s42, 0x800
	s_addc_u32 s43, s43, 0
	global_load_dwordx4 v[64:67], v144, s[24:25] offset:0
	global_load_dwordx4 v[68:71], v144, s[24:25] offset:1024
	global_load_dwordx4 v[72:75], v144, s[24:25] offset:2048
	global_load_dwordx4 v[76:79], v144, s[24:25] offset:3072
	global_load_dwordx4 v[80:83], v144, s[26:27] offset:0
	global_load_dwordx4 v[84:87], v144, s[26:27] offset:1024
	global_load_dwordx4 v[88:91], v144, s[26:27] offset:2048
	global_load_dwordx4 v[92:95], v144, s[26:27] offset:3072
	s_add_u32 s24, s24, 0x1000
	s_addc_u32 s25, s25, 0
	s_add_u32 s26, s26, 0x1000
	s_addc_u32 s27, s27, 0
	s_waitcnt vmcnt(32)
; __device__ __forceinline__ void phase_rowpass(const Ctx& p, const float* F, int base_is_x, float alpha, const float* gpost, const float* gnext, bf16_t* XN, const float* PART, int nsplit) {
;     ...
;         float s = 0.f;
; #pragma unroll
;         for (int j = 0; j < 4; ++j) s += (f[j].x * f[j].x + f[j].y * f[j].y) + (f[j].z * f[j].z + f[j].w * f[j].w);
;         const float rs = alpha / sqrtf(wave_sum_fast(s) * (1.f / DM) + EPS);
;         float s2 = 0.f;
; #pragma unroll
;         for (int j = 0; j < 4; ++j) { b[j] = b[j] + f[j] * rs * gp[j]; s2 += (b[j].x * b[j].x + b[j].y * b[j].y) + (b[j].z * b[j].z + b[j].w * b[j].w);
;             ((f32x4*)(H + (size_t)m * DM))[lane + 64 * j] = b[j]; }
;         if (gnext) {
;             const float r2 = 1.f / sqrtf(wave_sum_fast(s2) * (1.f / DM) + EPS);
	v_mul_f32_e32 v96, v1, v1
	v_mul_f32_e32 v98, v3, v3
	v_fmac_f32_e32 v96, v0, v0
	v_fmac_f32_e32 v98, v2, v2
	v_add_f32_e32 v96, v96, v98
	v_mul_f32_e32 v97, v5, v5
	v_mul_f32_e32 v98, v7, v7
	v_fmac_f32_e32 v97, v4, v4
	v_fmac_f32_e32 v98, v6, v6
	v_add_f32_e32 v97, v97, v98
	v_add_f32_e32 v96, v97, v96
	v_mul_f32_e32 v97, v9, v9
	v_mul_f32_e32 v98, v11, v11
	v_fmac_f32_e32 v97, v8, v8
	v_fmac_f32_e32 v98, v10, v10
	v_add_f32_e32 v97, v97, v98
	v_add_f32_e32 v96, v97, v96
	v_mul_f32_e32 v97, v13, v13
	v_mul_f32_e32 v98, v15, v15
	v_fmac_f32_e32 v97, v12, v12
	v_fmac_f32_e32 v98, v14, v14
	v_add_f32_e32 v97, v97, v98
	v_add_f32_e32 v96, v97, v96
	s_nop 1
	v_add_f32_dpp v96, v96, v96 quad_perm:[1,0,3,2] row_mask:0xf bank_mask:0xf bound_ctrl:1
	s_nop 1
	v_add_f32_dpp v96, v96, v96 quad_perm:[2,3,0,1] row_mask:0xf bank_mask:0xf bound_ctrl:1
	s_nop 1
	v_add_f32_dpp v96, v96, v96 row_half_mirror row_mask:0xf bank_mask:0xf bound_ctrl:1
	s_nop 1
	v_add_f32_dpp v96, v96, v96 row_mirror row_mask:0xf bank_mask:0xf bound_ctrl:1
	v_mov_b32_e32 v97, v96
	s_nop 1
	v_permlane16_swap_b32_e32 v96, v97
	v_add_f32_e32 v96, v96, v97
	v_mov_b32_e32 v97, v96
	s_nop 1
	v_permlane32_swap_b32_e32 v96, v97
	v_add_f32_e32 v96, v96, v97
	v_fmamk_f32 v96, v96, 0x3a800000, v146
	v_mul_f32_e32 v97, 0x4f800000, v96
	v_cmp_gt_f32_e32 vcc, s33, v96
	s_nop 1
	v_cndmask_b32_e32 v96, v96, v97, vcc
	v_sqrt_f32_e32 v97, v96
	s_nop 0
	v_add_u32_e32 v98, -1, v97
	v_fma_f32 v99, -v98, v97, v96
	v_cmp_ge_f32_e64 s[4:5], 0, v99
	v_add_u32_e32 v99, 1, v97
	s_nop 0
	v_cndmask_b32_e64 v98, v97, v98, s[4:5]
	v_fma_f32 v97, -v99, v97, v96
	v_cmp_lt_f32_e64 s[4:5], 0, v97
	s_nop 1
	v_cndmask_b32_e64 v97, v98, v99, s[4:5]
	v_mul_f32_e32 v98, 0x37800000, v97
	v_cndmask_b32_e32 v97, v97, v98, vcc
	v_cmp_class_f32_e32 vcc, v96, v147
	s_nop 1
	v_cndmask_b32_e32 v96, v97, v96, vcc
	v_div_scale_f32 v97, s[4:5], v96, v96, 0.5
	v_rcp_f32_e32 v98, v97
	s_nop 0
	v_fma_f32 v99, -v97, v98, 1.0
	v_fmac_f32_e32 v98, v99, v98
	v_div_scale_f32 v99, vcc, 0.5, v96, 0.5
	v_mul_f32_e32 v100, v99, v98
	v_fma_f32 v101, -v97, v100, v99
	v_fmac_f32_e32 v100, v101, v98
	v_fma_f32 v97, -v97, v100, v99
	v_div_fmas_f32 v97, v97, v98, v100
	v_div_fixup_f32 v96, v97, v96, 0.5
	v_mul_f32_e32 v0, v0, v96
	v_mul_f32_e32 v1, v1, v96
	v_mul_f32_e32 v2, v2, v96
	v_mul_f32_e32 v3, v3, v96
	v_mul_f32_e32 v4, v4, v96
	v_mul_f32_e32 v5, v5, v96
	v_mul_f32_e32 v6, v6, v96
	v_mul_f32_e32 v7, v7, v96
	v_mul_f32_e32 v8, v8, v96
	v_mul_f32_e32 v9, v9, v96
	v_mul_f32_e32 v10, v10, v96
	v_mul_f32_e32 v11, v11, v96
	v_mul_f32_e32 v12, v12, v96
	v_mul_f32_e32 v13, v13, v96
	v_mul_f32_e32 v14, v14, v96
	v_mul_f32_e32 v15, v15, v96
	v_fmac_f32_e32 v16, v112, v0
	v_fmac_f32_e32 v17, v113, v1
	v_fmac_f32_e32 v18, v114, v2
	v_fmac_f32_e32 v19, v115, v3
	v_fmac_f32_e32 v20, v116, v4
	v_fmac_f32_e32 v21, v117, v5
	v_fmac_f32_e32 v22, v118, v6
	v_fmac_f32_e32 v23, v119, v7
	v_fmac_f32_e32 v24, v120, v8
	v_fmac_f32_e32 v25, v121, v9
	v_fmac_f32_e32 v26, v122, v10
	v_fmac_f32_e32 v27, v123, v11
	v_fmac_f32_e32 v28, v124, v12
	v_fmac_f32_e32 v29, v125, v13
	v_fmac_f32_e32 v30, v126, v14
	v_fmac_f32_e32 v31, v127, v15
	global_store_dwordx4 v144, v[16:19], s[40:41] offset:0
	global_store_dwordx4 v144, v[20:23], s[40:41] offset:1024
	global_store_dwordx4 v144, v[24:27], s[40:41] offset:2048
	global_store_dwordx4 v144, v[28:31], s[40:41] offset:3072
	v_mul_f32_e32 v96, v17, v17
	v_mul_f32_e32 v98, v19, v19
	v_fmac_f32_e32 v96, v16, v16
	v_fmac_f32_e32 v98, v18, v18
	v_add_f32_e32 v96, v96, v98
	v_mul_f32_e32 v97, v21, v21
	v_mul_f32_e32 v98, v23, v23
	v_fmac_f32_e32 v97, v20, v20
	v_fmac_f32_e32 v98, v22, v22
	v_add_f32_e32 v97, v97, v98
	v_add_f32_e32 v96, v97, v96
	v_mul_f32_e32 v97, v25, v25
	v_mul_f32_e32 v98, v27, v27
	v_fmac_f32_e32 v97, v24, v24
	v_fmac_f32_e32 v98, v26, v26
	v_add_f32_e32 v97, v97, v98
	v_add_f32_e32 v96, v97, v96
	v_mul_f32_e32 v97, v29, v29
	v_mul_f32_e32 v98, v31, v31
	v_fmac_f32_e32 v97, v28, v28
	v_fmac_f32_e32 v98, v30, v30
	v_add_f32_e32 v97, v97, v98
	v_add_f32_e32 v96, v97, v96
	s_nop 1
	v_add_f32_dpp v96, v96, v96 quad_perm:[1,0,3,2] row_mask:0xf bank_mask:0xf bound_ctrl:1
	s_nop 1
	v_add_f32_dpp v96, v96, v96 quad_perm:[2,3,0,1] row_mask:0xf bank_mask:0xf bound_ctrl:1
	s_nop 1
	v_add_f32_dpp v96, v96, v96 row_half_mirror row_mask:0xf bank_mask:0xf bound_ctrl:1
	s_nop 1
	v_add_f32_dpp v96, v96, v96 row_mirror row_mask:0xf bank_mask:0xf bound_ctrl:1
	v_mov_b32_e32 v97, v96
	s_nop 1
	v_permlane16_swap_b32_e32 v96, v97
	v_add_f32_e32 v96, v96, v97
	v_mov_b32_e32 v97, v96
	s_nop 1
	v_permlane32_swap_b32_e32 v96, v97
	v_add_f32_e32 v96, v96, v97
	v_fmamk_f32 v96, v96, 0x3a800000, v146
	v_mul_f32_e32 v97, 0x4f800000, v96
	v_cmp_gt_f32_e32 vcc, s33, v96
	s_nop 1
	v_cndmask_b32_e32 v96, v96, v97, vcc
	v_sqrt_f32_e32 v97, v96
	s_nop 0
	v_add_u32_e32 v98, -1, v97
	v_fma_f32 v99, -v98, v97, v96
	v_cmp_ge_f32_e64 s[4:5], 0, v99
	v_add_u32_e32 v99, 1, v97
	s_nop 0
	v_cndmask_b32_e64 v98, v97, v98, s[4:5]
	v_fma_f32 v97, -v99, v97, v96
	v_cmp_lt_f32_e64 s[4:5], 0, v97
	s_nop 1
	v_cndmask_b32_e64 v97, v98, v99, s[4:5]
	v_mul_f32_e32 v98, 0x37800000, v97
	v_cndmask_b32_e32 v97, v97, v98, vcc
	v_cmp_class_f32_e32 vcc, v96, v147
	s_nop 1
	v_cndmask_b32_e32 v96, v97, v96, vcc
	v_div_scale_f32 v97, s[4:5], v96, v96, 1.0
	v_rcp_f32_e32 v98, v97
	s_nop 0
	v_fma_f32 v99, -v97, v98, 1.0
	v_fmac_f32_e32 v98, v99, v98
	v_div_scale_f32 v99, vcc, 1.0, v96, 1.0
	v_mul_f32_e32 v100, v99, v98
	v_fma_f32 v101, -v97, v100, v99
	v_fmac_f32_e32 v100, v101, v98
	v_fma_f32 v97, -v97, v100, v99
	v_div_fmas_f32 v97, v97, v98, v100
	v_div_fixup_f32 v96, v97, v96, 1.0
; __device__ __forceinline__ unsigned pk2(float lo, float hi) { f32x2 v = {lo, hi}; bf16x2_t b = __builtin_convertvector(v, bf16x2_t); return __builtin_bit_cast(unsigned, b); }
; __device__ __forceinline__ void phase_rowpass(const Ctx& p, const float* F, int base_is_x, float alpha, const float* gpost, const float* gnext, bf16_t* XN, const float* PART, int nsplit) {
;     ...
;         float s = 0.f;
; #pragma unroll
;         for (int j = 0; j < 4; ++j) s += (f[j].x * f[j].x + f[j].y * f[j].y) + (f[j].z * f[j].z + f[j].w * f[j].w);
;         const float rs = alpha / sqrtf(wave_sum_fast(s) * (1.f / DM) + EPS);
;         float s2 = 0.f;
; #pragma unroll
;         for (int j = 0; j < 4; ++j) { b[j] = b[j] + f[j] * rs * gp[j]; s2 += (b[j].x * b[j].x + b[j].y * b[j].y) + (b[j].z * b[j].z + b[j].w * b[j].w);
;             ((f32x4*)(H + (size_t)m * DM))[lane + 64 * j] = b[j]; }
;     ...
;             u32x2* o8 = (u32x2*)(XN + (size_t)m * DM) + lane;
; #pragma unroll
;             for (int j = 0; j < 4; ++j) { u32x2 w; w.x = pk2(b[j].x * r2 * gn[j].x, b[j].y * r2 * gn[j].y); w.y = pk2(b[j].z * r2 * gn[j].z, b[j].w * r2 * gn[j].w); o8[64 * j] = w; }
	v_mul_f32_e32 v0, v16, v96
	v_mul_f32_e32 v1, v17, v96
	v_mul_f32_e32 v2, v18, v96
	v_mul_f32_e32 v3, v19, v96
	v_mul_f32_e32 v4, v20, v96
	v_mul_f32_e32 v5, v21, v96
	v_mul_f32_e32 v6, v22, v96
	v_mul_f32_e32 v7, v23, v96
	v_mul_f32_e32 v8, v24, v96
	v_mul_f32_e32 v9, v25, v96
	v_mul_f32_e32 v10, v26, v96
	v_mul_f32_e32 v11, v27, v96
	v_mul_f32_e32 v12, v28, v96
	v_mul_f32_e32 v13, v29, v96
	v_mul_f32_e32 v14, v30, v96
	v_mul_f32_e32 v15, v31, v96
	v_mul_f32_e32 v0, v128, v0
	v_mul_f32_e32 v1, v129, v1
	v_mul_f32_e32 v2, v130, v2
	v_mul_f32_e32 v3, v131, v3
	v_mul_f32_e32 v4, v132, v4
	v_mul_f32_e32 v5, v133, v5
	v_mul_f32_e32 v6, v134, v6
	v_mul_f32_e32 v7, v135, v7
	v_mul_f32_e32 v8, v136, v8
	v_mul_f32_e32 v9, v137, v9
	v_mul_f32_e32 v10, v138, v10
	v_mul_f32_e32 v11, v139, v11
	v_mul_f32_e32 v12, v140, v12
	v_mul_f32_e32 v13, v141, v13
	v_mul_f32_e32 v14, v142, v14
	v_mul_f32_e32 v15, v143, v15
	v_cvt_pk_bf16_f32 v148, v0, v1
	v_cvt_pk_bf16_f32 v149, v2, v3
	global_store_dwordx2 v145, v[148:149], s[42:43] offset:0
	v_cvt_pk_bf16_f32 v150, v4, v5
	v_cvt_pk_bf16_f32 v151, v6, v7
	global_store_dwordx2 v145, v[150:151], s[42:43] offset:512
	v_cvt_pk_bf16_f32 v152, v8, v9
	v_cvt_pk_bf16_f32 v153, v10, v11
	global_store_dwordx2 v145, v[152:153], s[42:43] offset:1024
	v_cvt_pk_bf16_f32 v154, v12, v13
	v_cvt_pk_bf16_f32 v155, v14, v15
	global_store_dwordx2 v145, v[154:155], s[42:43] offset:1536
	s_add_u32 s40, s40, 0x1000
	s_addc_u32 s41, s41, 0
	s_add_u32 s42, s42, 0x800
	s_addc_u32 s43, s43, 0
	global_load_dwordx4 v[0:3], v144, s[24:25] offset:0
	global_load_dwordx4 v[4:7], v144, s[24:25] offset:1024
	global_load_dwordx4 v[8:11], v144, s[24:25] offset:2048
	global_load_dwordx4 v[12:15], v144, s[24:25] offset:3072
	global_load_dwordx4 v[16:19], v144, s[26:27] offset:0
	global_load_dwordx4 v[20:23], v144, s[26:27] offset:1024
	global_load_dwordx4 v[24:27], v144, s[26:27] offset:2048
	global_load_dwordx4 v[28:31], v144, s[26:27] offset:3072
	s_add_u32 s24, s24, 0x1000
	s_addc_u32 s25, s25, 0
	s_add_u32 s26, s26, 0x1000
	s_addc_u32 s27, s27, 0
	s_waitcnt vmcnt(32)
	v_mul_f32_e32 v96, v33, v33
	v_mul_f32_e32 v98, v35, v35
	v_fmac_f32_e32 v96, v32, v32
	v_fmac_f32_e32 v98, v34, v34
	v_add_f32_e32 v96, v96, v98
	v_mul_f32_e32 v97, v37, v37
	v_mul_f32_e32 v98, v39, v39
	v_fmac_f32_e32 v97, v36, v36
	v_fmac_f32_e32 v98, v38, v38
	v_add_f32_e32 v97, v97, v98
	v_add_f32_e32 v96, v97, v96
	v_mul_f32_e32 v97, v41, v41
	v_mul_f32_e32 v98, v43, v43
	v_fmac_f32_e32 v97, v40, v40
	v_fmac_f32_e32 v98, v42, v42
	v_add_f32_e32 v97, v97, v98
	v_add_f32_e32 v96, v97, v96
	v_mul_f32_e32 v97, v45, v45
	v_mul_f32_e32 v98, v47, v47
	v_fmac_f32_e32 v97, v44, v44
	v_fmac_f32_e32 v98, v46, v46
	v_add_f32_e32 v97, v97, v98
	v_add_f32_e32 v96, v97, v96
	s_nop 1
	v_add_f32_dpp v96, v96, v96 quad_perm:[1,0,3,2] row_mask:0xf bank_mask:0xf bound_ctrl:1
	s_nop 1
	v_add_f32_dpp v96, v96, v96 quad_perm:[2,3,0,1] row_mask:0xf bank_mask:0xf bound_ctrl:1
	s_nop 1
	v_add_f32_dpp v96, v96, v96 row_half_mirror row_mask:0xf bank_mask:0xf bound_ctrl:1
	s_nop 1
	v_add_f32_dpp v96, v96, v96 row_mirror row_mask:0xf bank_mask:0xf bound_ctrl:1
	v_mov_b32_e32 v97, v96
	s_nop 1
	v_permlane16_swap_b32_e32 v96, v97
	v_add_f32_e32 v96, v96, v97
	v_mov_b32_e32 v97, v96
	s_nop 1
	v_permlane32_swap_b32_e32 v96, v97
	v_add_f32_e32 v96, v96, v97
	v_fmamk_f32 v96, v96, 0x3a800000, v146
	v_mul_f32_e32 v97, 0x4f800000, v96
	v_cmp_gt_f32_e32 vcc, s33, v96
	s_nop 1
	v_cndmask_b32_e32 v96, v96, v97, vcc
	v_sqrt_f32_e32 v97, v96
	s_nop 0
	v_add_u32_e32 v98, -1, v97
	v_fma_f32 v99, -v98, v97, v96
	v_cmp_ge_f32_e64 s[4:5], 0, v99
	v_add_u32_e32 v99, 1, v97
	s_nop 0
	v_cndmask_b32_e64 v98, v97, v98, s[4:5]
	v_fma_f32 v97, -v99, v97, v96
	v_cmp_lt_f32_e64 s[4:5], 0, v97
	s_nop 1
	v_cndmask_b32_e64 v97, v98, v99, s[4:5]
	v_mul_f32_e32 v98, 0x37800000, v97
	v_cndmask_b32_e32 v97, v97, v98, vcc
	v_cmp_class_f32_e32 vcc, v96, v147
	s_nop 1
	v_cndmask_b32_e32 v96, v97, v96, vcc
	v_div_scale_f32 v97, s[4:5], v96, v96, 0.5
	v_rcp_f32_e32 v98, v97
	s_nop 0
	v_fma_f32 v99, -v97, v98, 1.0
	v_fmac_f32_e32 v98, v99, v98
	v_div_scale_f32 v99, vcc, 0.5, v96, 0.5
	v_mul_f32_e32 v100, v99, v98
	v_fma_f32 v101, -v97, v100, v99
	v_fmac_f32_e32 v100, v101, v98
	v_fma_f32 v97, -v97, v100, v99
	v_div_fmas_f32 v97, v97, v98, v100
	v_div_fixup_f32 v96, v97, v96, 0.5
	v_mul_f32_e32 v32, v32, v96
	v_mul_f32_e32 v33, v33, v96
	v_mul_f32_e32 v34, v34, v96
	v_mul_f32_e32 v35, v35, v96
	v_mul_f32_e32 v36, v36, v96
	v_mul_f32_e32 v37, v37, v96
	v_mul_f32_e32 v38, v38, v96
	v_mul_f32_e32 v39, v39, v96
	v_mul_f32_e32 v40, v40, v96
	v_mul_f32_e32 v41, v41, v96
	v_mul_f32_e32 v42, v42, v96
	v_mul_f32_e32 v43, v43, v96
	v_mul_f32_e32 v44, v44, v96
	v_mul_f32_e32 v45, v45, v96
	v_mul_f32_e32 v46, v46, v96
	v_mul_f32_e32 v47, v47, v96
	v_fmac_f32_e32 v48, v112, v32
	v_fmac_f32_e32 v49, v113, v33
	v_fmac_f32_e32 v50, v114, v34
	v_fmac_f32_e32 v51, v115, v35
	v_fmac_f32_e32 v52, v116, v36
	v_fmac_f32_e32 v53, v117, v37
	v_fmac_f32_e32 v54, v118, v38
	v_fmac_f32_e32 v55, v119, v39
	v_fmac_f32_e32 v56, v120, v40
	v_fmac_f32_e32 v57, v121, v41
	v_fmac_f32_e32 v58, v122, v42
	v_fmac_f32_e32 v59, v123, v43
	v_fmac_f32_e32 v60, v124, v44
	v_fmac_f32_e32 v61, v125, v45
	v_fmac_f32_e32 v62, v126, v46
	v_fmac_f32_e32 v63, v127, v47
	global_store_dwordx4 v144, v[48:51], s[40:41] offset:0
	global_store_dwordx4 v144, v[52:55], s[40:41] offset:1024
	global_store_dwordx4 v144, v[56:59], s[40:41] offset:2048
	global_store_dwordx4 v144, v[60:63], s[40:41] offset:3072
	v_mul_f32_e32 v96, v49, v49
	v_mul_f32_e32 v98, v51, v51
	v_fmac_f32_e32 v96, v48, v48
; __device__ __forceinline__ unsigned pk2(float lo, float hi) { f32x2 v = {lo, hi}; bf16x2_t b = __builtin_convertvector(v, bf16x2_t); return __builtin_bit_cast(unsigned, b); }
; __device__ __forceinline__ void phase_rowpass(const Ctx& p, const float* F, int base_is_x, float alpha, const float* gpost, const float* gnext, bf16_t* XN, const float* PART, int nsplit) {
;     ...
;             const float r2 = 1.f / sqrtf(wave_sum_fast(s2) * (1.f / DM) + EPS);
;             u32x2* o8 = (u32x2*)(XN + (size_t)m * DM) + lane;
; #pragma unroll
;             for (int j = 0; j < 4; ++j) { u32x2 w; w.x = pk2(b[j].x * r2 * gn[j].x, b[j].y * r2 * gn[j].y); w.y = pk2(b[j].z * r2 * gn[j].z, b[j].w * r2 * gn[j].w); o8[64 * j] = w; }
	v_fmac_f32_e32 v98, v50, v50
	v_add_f32_e32 v96, v96, v98
	v_mul_f32_e32 v97, v53, v53
	v_mul_f32_e32 v98, v55, v55
	v_fmac_f32_e32 v97, v52, v52
	v_fmac_f32_e32 v98, v54, v54
	v_add_f32_e32 v97, v97, v98
	v_add_f32_e32 v96, v97, v96
	v_mul_f32_e32 v97, v57, v57
	v_mul_f32_e32 v98, v59, v59
	v_fmac_f32_e32 v97, v56, v56
	v_fmac_f32_e32 v98, v58, v58
	v_add_f32_e32 v97, v97, v98
	v_add_f32_e32 v96, v97, v96
	v_mul_f32_e32 v97, v61, v61
	v_mul_f32_e32 v98, v63, v63
	v_fmac_f32_e32 v97, v60, v60
	v_fmac_f32_e32 v98, v62, v62
	v_add_f32_e32 v97, v97, v98
	v_add_f32_e32 v96, v97, v96
	s_nop 1
	v_add_f32_dpp v96, v96, v96 quad_perm:[1,0,3,2] row_mask:0xf bank_mask:0xf bound_ctrl:1
	s_nop 1
	v_add_f32_dpp v96, v96, v96 quad_perm:[2,3,0,1] row_mask:0xf bank_mask:0xf bound_ctrl:1
	s_nop 1
	v_add_f32_dpp v96, v96, v96 row_half_mirror row_mask:0xf bank_mask:0xf bound_ctrl:1
	s_nop 1
	v_add_f32_dpp v96, v96, v96 row_mirror row_mask:0xf bank_mask:0xf bound_ctrl:1
	v_mov_b32_e32 v97, v96
	s_nop 1
	v_permlane16_swap_b32_e32 v96, v97
	v_add_f32_e32 v96, v96, v97
	v_mov_b32_e32 v97, v96
	s_nop 1
	v_permlane32_swap_b32_e32 v96, v97
	v_add_f32_e32 v96, v96, v97
	v_fmamk_f32 v96, v96, 0x3a800000, v146
	v_mul_f32_e32 v97, 0x4f800000, v96
	v_cmp_gt_f32_e32 vcc, s33, v96
	s_nop 1
	v_cndmask_b32_e32 v96, v96, v97, vcc
	v_sqrt_f32_e32 v97, v96
	s_nop 0
	v_add_u32_e32 v98, -1, v97
	v_fma_f32 v99, -v98, v97, v96
	v_cmp_ge_f32_e64 s[4:5], 0, v99
	v_add_u32_e32 v99, 1, v97
	s_nop 0
	v_cndmask_b32_e64 v98, v97, v98, s[4:5]
	v_fma_f32 v97, -v99, v97, v96
	v_cmp_lt_f32_e64 s[4:5], 0, v97
	s_nop 1
	v_cndmask_b32_e64 v97, v98, v99, s[4:5]
	v_mul_f32_e32 v98, 0x37800000, v97
	v_cndmask_b32_e32 v97, v97, v98, vcc
	v_cmp_class_f32_e32 vcc, v96, v147
	s_nop 1
	v_cndmask_b32_e32 v96, v97, v96, vcc
	v_div_scale_f32 v97, s[4:5], v96, v96, 1.0
	v_rcp_f32_e32 v98, v97
	s_nop 0
	v_fma_f32 v99, -v97, v98, 1.0
	v_fmac_f32_e32 v98, v99, v98
	v_div_scale_f32 v99, vcc, 1.0, v96, 1.0
	v_mul_f32_e32 v100, v99, v98
	v_fma_f32 v101, -v97, v100, v99
	v_fmac_f32_e32 v100, v101, v98
	v_fma_f32 v97, -v97, v100, v99
	v_div_fmas_f32 v97, v97, v98, v100
	v_div_fixup_f32 v96, v97, v96, 1.0
	v_mul_f32_e32 v32, v48, v96
	v_mul_f32_e32 v33, v49, v96
	v_mul_f32_e32 v34, v50, v96
	v_mul_f32_e32 v35, v51, v96
	v_mul_f32_e32 v36, v52, v96
	v_mul_f32_e32 v37, v53, v96
	v_mul_f32_e32 v38, v54, v96
	v_mul_f32_e32 v39, v55, v96
	v_mul_f32_e32 v40, v56, v96
	v_mul_f32_e32 v41, v57, v96
	v_mul_f32_e32 v42, v58, v96
	v_mul_f32_e32 v43, v59, v96
	v_mul_f32_e32 v44, v60, v96
	v_mul_f32_e32 v45, v61, v96
	v_mul_f32_e32 v46, v62, v96
	v_mul_f32_e32 v47, v63, v96
	v_mul_f32_e32 v32, v128, v32
	v_mul_f32_e32 v33, v129, v33
	v_mul_f32_e32 v34, v130, v34
	v_mul_f32_e32 v35, v131, v35
	v_mul_f32_e32 v36, v132, v36
	v_mul_f32_e32 v37, v133, v37
	v_mul_f32_e32 v38, v134, v38
	v_mul_f32_e32 v39, v135, v39
	v_mul_f32_e32 v40, v136, v40
	v_mul_f32_e32 v41, v137, v41
	v_mul_f32_e32 v42, v138, v42
	v_mul_f32_e32 v43, v139, v43
	v_mul_f32_e32 v44, v140, v44
	v_mul_f32_e32 v45, v141, v45
	v_mul_f32_e32 v46, v142, v46
	v_mul_f32_e32 v47, v143, v47
	v_cvt_pk_bf16_f32 v148, v32, v33
	v_cvt_pk_bf16_f32 v149, v34, v35
	global_store_dwordx2 v145, v[148:149], s[42:43] offset:0
	v_cvt_pk_bf16_f32 v150, v36, v37
	v_cvt_pk_bf16_f32 v151, v38, v39
	global_store_dwordx2 v145, v[150:151], s[42:43] offset:512
	v_cvt_pk_bf16_f32 v152, v40, v41
	v_cvt_pk_bf16_f32 v153, v42, v43
	global_store_dwordx2 v145, v[152:153], s[42:43] offset:1024
	v_cvt_pk_bf16_f32 v154, v44, v45
	v_cvt_pk_bf16_f32 v155, v46, v47
	global_store_dwordx2 v145, v[154:155], s[42:43] offset:1536
	s_add_u32 s40, s40, 0x1000
	s_addc_u32 s41, s41, 0
	s_add_u32 s42, s42, 0x800
	s_addc_u32 s43, s43, 0
	global_load_dwordx4 v[32:35], v144, s[24:25] offset:0
	global_load_dwordx4 v[36:39], v144, s[24:25] offset:1024
	global_load_dwordx4 v[40:43], v144, s[24:25] offset:2048
	global_load_dwordx4 v[44:47], v144, s[24:25] offset:3072
	global_load_dwordx4 v[48:51], v144, s[26:27] offset:0
	global_load_dwordx4 v[52:55], v144, s[26:27] offset:1024
	global_load_dwordx4 v[56:59], v144, s[26:27] offset:2048
	global_load_dwordx4 v[60:63], v144, s[26:27] offset:3072
	s_add_u32 s24, s24, 0x1000
	s_addc_u32 s25, s25, 0
	s_add_u32 s26, s26, 0x1000
	s_addc_u32 s27, s27, 0
	s_waitcnt vmcnt(32)
; __device__ __forceinline__ void phase_rowpass(const Ctx& p, const float* F, int base_is_x, float alpha, const float* gpost, const float* gnext, bf16_t* XN, const float* PART, int nsplit) {
;     ...
;         float s = 0.f;
; #pragma unroll
;         for (int j = 0; j < 4; ++j) s += (f[j].x * f[j].x + f[j].y * f[j].y) + (f[j].z * f[j].z + f[j].w * f[j].w);
;         const float rs = alpha / sqrtf(wave_sum_fast(s) * (1.f / DM) + EPS);
;         float s2 = 0.f;
; #pragma unroll
;         for (int j = 0; j < 4; ++j) { b[j] = b[j] + f[j] * rs * gp[j]; s2 += (b[j].x * b[j].x + b[j].y * b[j].y) + (b[j].z * b[j].z + b[j].w * b[j].w);
;             ((f32x4*)(H + (size_t)m * DM))[lane + 64 * j] = b[j]; }
;         if (gnext) {
;             const float r2 = 1.f / sqrtf(wave_sum_fast(s2) * (1.f / DM) + EPS);
	v_mul_f32_e32 v96, v65, v65
	v_mul_f32_e32 v98, v67, v67
	v_fmac_f32_e32 v96, v64, v64
	v_fmac_f32_e32 v98, v66, v66
	v_add_f32_e32 v96, v96, v98
	v_mul_f32_e32 v97, v69, v69
	v_mul_f32_e32 v98, v71, v71
	v_fmac_f32_e32 v97, v68, v68
	v_fmac_f32_e32 v98, v70, v70
	v_add_f32_e32 v97, v97, v98
	v_add_f32_e32 v96, v97, v96
	v_mul_f32_e32 v97, v73, v73
	v_mul_f32_e32 v98, v75, v75
	v_fmac_f32_e32 v97, v72, v72
	v_fmac_f32_e32 v98, v74, v74
	v_add_f32_e32 v97, v97, v98
	v_add_f32_e32 v96, v97, v96
	v_mul_f32_e32 v97, v77, v77
	v_mul_f32_e32 v98, v79, v79
	v_fmac_f32_e32 v97, v76, v76
	v_fmac_f32_e32 v98, v78, v78
	v_add_f32_e32 v97, v97, v98
	v_add_f32_e32 v96, v97, v96
	s_nop 1
	v_add_f32_dpp v96, v96, v96 quad_perm:[1,0,3,2] row_mask:0xf bank_mask:0xf bound_ctrl:1
	s_nop 1
	v_add_f32_dpp v96, v96, v96 quad_perm:[2,3,0,1] row_mask:0xf bank_mask:0xf bound_ctrl:1
	s_nop 1
	v_add_f32_dpp v96, v96, v96 row_half_mirror row_mask:0xf bank_mask:0xf bound_ctrl:1
	s_nop 1
	v_add_f32_dpp v96, v96, v96 row_mirror row_mask:0xf bank_mask:0xf bound_ctrl:1
	v_mov_b32_e32 v97, v96
	s_nop 1
	v_permlane16_swap_b32_e32 v96, v97
	v_add_f32_e32 v96, v96, v97
	v_mov_b32_e32 v97, v96
	s_nop 1
	v_permlane32_swap_b32_e32 v96, v97
	v_add_f32_e32 v96, v96, v97
	v_fmamk_f32 v96, v96, 0x3a800000, v146
	v_mul_f32_e32 v97, 0x4f800000, v96
	v_cmp_gt_f32_e32 vcc, s33, v96
	s_nop 1
	v_cndmask_b32_e32 v96, v96, v97, vcc
	v_sqrt_f32_e32 v97, v96
	s_nop 0
	v_add_u32_e32 v98, -1, v97
	v_fma_f32 v99, -v98, v97, v96
	v_cmp_ge_f32_e64 s[4:5], 0, v99
	v_add_u32_e32 v99, 1, v97
	s_nop 0
	v_cndmask_b32_e64 v98, v97, v98, s[4:5]
	v_fma_f32 v97, -v99, v97, v96
	v_cmp_lt_f32_e64 s[4:5], 0, v97
	s_nop 1
	v_cndmask_b32_e64 v97, v98, v99, s[4:5]
	v_mul_f32_e32 v98, 0x37800000, v97
	v_cndmask_b32_e32 v97, v97, v98, vcc
	v_cmp_class_f32_e32 vcc, v96, v147
	s_nop 1
	v_cndmask_b32_e32 v96, v97, v96, vcc
	v_div_scale_f32 v97, s[4:5], v96, v96, 0.5
	v_rcp_f32_e32 v98, v97
	s_nop 0
	v_fma_f32 v99, -v97, v98, 1.0
	v_fmac_f32_e32 v98, v99, v98
	v_div_scale_f32 v99, vcc, 0.5, v96, 0.5
	v_mul_f32_e32 v100, v99, v98
	v_fma_f32 v101, -v97, v100, v99
	v_fmac_f32_e32 v100, v101, v98
	v_fma_f32 v97, -v97, v100, v99
	v_div_fmas_f32 v97, v97, v98, v100
	v_div_fixup_f32 v96, v97, v96, 0.5
	v_mul_f32_e32 v64, v64, v96
	v_mul_f32_e32 v65, v65, v96
	v_mul_f32_e32 v66, v66, v96
	v_mul_f32_e32 v67, v67, v96
	v_mul_f32_e32 v68, v68, v96
	v_mul_f32_e32 v69, v69, v96
	v_mul_f32_e32 v70, v70, v96
	v_mul_f32_e32 v71, v71, v96
	v_mul_f32_e32 v72, v72, v96
	v_mul_f32_e32 v73, v73, v96
	v_mul_f32_e32 v74, v74, v96
	v_mul_f32_e32 v75, v75, v96
	v_mul_f32_e32 v76, v76, v96
	v_mul_f32_e32 v77, v77, v96
	v_mul_f32_e32 v78, v78, v96
	v_mul_f32_e32 v79, v79, v96
	v_fmac_f32_e32 v80, v112, v64
	v_fmac_f32_e32 v81, v113, v65
	v_fmac_f32_e32 v82, v114, v66
	v_fmac_f32_e32 v83, v115, v67
	v_fmac_f32_e32 v84, v116, v68
	v_fmac_f32_e32 v85, v117, v69
	v_fmac_f32_e32 v86, v118, v70
	v_fmac_f32_e32 v87, v119, v71
	v_fmac_f32_e32 v88, v120, v72
	v_fmac_f32_e32 v89, v121, v73
	v_fmac_f32_e32 v90, v122, v74
	v_fmac_f32_e32 v91, v123, v75
	v_fmac_f32_e32 v92, v124, v76
	v_fmac_f32_e32 v93, v125, v77
	v_fmac_f32_e32 v94, v126, v78
	v_fmac_f32_e32 v95, v127, v79
	global_store_dwordx4 v144, v[80:83], s[40:41] offset:0
	global_store_dwordx4 v144, v[84:87], s[40:41] offset:1024
	global_store_dwordx4 v144, v[88:91], s[40:41] offset:2048
	global_store_dwordx4 v144, v[92:95], s[40:41] offset:3072
	v_mul_f32_e32 v96, v81, v81
	v_mul_f32_e32 v98, v83, v83
	v_fmac_f32_e32 v96, v80, v80
	v_fmac_f32_e32 v98, v82, v82
	v_add_f32_e32 v96, v96, v98
	v_mul_f32_e32 v97, v85, v85
	v_mul_f32_e32 v98, v87, v87
	v_fmac_f32_e32 v97, v84, v84
	v_fmac_f32_e32 v98, v86, v86
	v_add_f32_e32 v97, v97, v98
	v_add_f32_e32 v96, v97, v96
	v_mul_f32_e32 v97, v89, v89
	v_mul_f32_e32 v98, v91, v91
	v_fmac_f32_e32 v97, v88, v88
	v_fmac_f32_e32 v98, v90, v90
	v_add_f32_e32 v97, v97, v98
	v_add_f32_e32 v96, v97, v96
	v_mul_f32_e32 v97, v93, v93
	v_mul_f32_e32 v98, v95, v95
	v_fmac_f32_e32 v97, v92, v92
	v_fmac_f32_e32 v98, v94, v94
	v_add_f32_e32 v97, v97, v98
	v_add_f32_e32 v96, v97, v96
	s_nop 1
	v_add_f32_dpp v96, v96, v96 quad_perm:[1,0,3,2] row_mask:0xf bank_mask:0xf bound_ctrl:1
	s_nop 1
	v_add_f32_dpp v96, v96, v96 quad_perm:[2,3,0,1] row_mask:0xf bank_mask:0xf bound_ctrl:1
	s_nop 1
	v_add_f32_dpp v96, v96, v96 row_half_mirror row_mask:0xf bank_mask:0xf bound_ctrl:1
	s_nop 1
	v_add_f32_dpp v96, v96, v96 row_mirror row_mask:0xf bank_mask:0xf bound_ctrl:1
	v_mov_b32_e32 v97, v96
	s_nop 1
	v_permlane16_swap_b32_e32 v96, v97
	v_add_f32_e32 v96, v96, v97
	v_mov_b32_e32 v97, v96
	s_nop 1
	v_permlane32_swap_b32_e32 v96, v97
	v_add_f32_e32 v96, v96, v97
	v_fmamk_f32 v96, v96, 0x3a800000, v146
	v_mul_f32_e32 v97, 0x4f800000, v96
	v_cmp_gt_f32_e32 vcc, s33, v96
	s_nop 1
	v_cndmask_b32_e32 v96, v96, v97, vcc
	v_sqrt_f32_e32 v97, v96
	s_nop 0
	v_add_u32_e32 v98, -1, v97
	v_fma_f32 v99, -v98, v97, v96
	v_cmp_ge_f32_e64 s[4:5], 0, v99
	v_add_u32_e32 v99, 1, v97
	s_nop 0
	v_cndmask_b32_e64 v98, v97, v98, s[4:5]
	v_fma_f32 v97, -v99, v97, v96
	v_cmp_lt_f32_e64 s[4:5], 0, v97
	s_nop 1
	v_cndmask_b32_e64 v97, v98, v99, s[4:5]
	v_mul_f32_e32 v98, 0x37800000, v97
	v_cndmask_b32_e32 v97, v97, v98, vcc
	v_cmp_class_f32_e32 vcc, v96, v147
	s_nop 1
	v_cndmask_b32_e32 v96, v97, v96, vcc
	v_div_scale_f32 v97, s[4:5], v96, v96, 1.0
	v_rcp_f32_e32 v98, v97
	s_nop 0
	v_fma_f32 v99, -v97, v98, 1.0
	v_fmac_f32_e32 v98, v99, v98
	v_div_scale_f32 v99, vcc, 1.0, v96, 1.0
	v_mul_f32_e32 v100, v99, v98
	v_fma_f32 v101, -v97, v100, v99
	v_fmac_f32_e32 v100, v101, v98
	v_fma_f32 v97, -v97, v100, v99
; __device__ __forceinline__ unsigned pk2(float lo, float hi) { f32x2 v = {lo, hi}; bf16x2_t b = __builtin_convertvector(v, bf16x2_t); return __builtin_bit_cast(unsigned, b); }
; __device__ __forceinline__ void phase_rowpass(const Ctx& p, const float* F, int base_is_x, float alpha, const float* gpost, const float* gnext, bf16_t* XN, const float* PART, int nsplit) {
;     ...
;         float s = 0.f;
; #pragma unroll
;         for (int j = 0; j < 4; ++j) s += (f[j].x * f[j].x + f[j].y * f[j].y) + (f[j].z * f[j].z + f[j].w * f[j].w);
;         const float rs = alpha / sqrtf(wave_sum_fast(s) * (1.f / DM) + EPS);
;         float s2 = 0.f;
; #pragma unroll
;         for (int j = 0; j < 4; ++j) { b[j] = b[j] + f[j] * rs * gp[j]; s2 += (b[j].x * b[j].x + b[j].y * b[j].y) + (b[j].z * b[j].z + b[j].w * b[j].w);
;             ((f32x4*)(H + (size_t)m * DM))[lane + 64 * j] = b[j]; }
;     ...
;             u32x2* o8 = (u32x2*)(XN + (size_t)m * DM) + lane;
; #pragma unroll
;             for (int j = 0; j < 4; ++j) { u32x2 w; w.x = pk2(b[j].x * r2 * gn[j].x, b[j].y * r2 * gn[j].y); w.y = pk2(b[j].z * r2 * gn[j].z, b[j].w * r2 * gn[j].w); o8[64 * j] = w; }
	v_div_fmas_f32 v97, v97, v98, v100
	v_div_fixup_f32 v96, v97, v96, 1.0
	v_mul_f32_e32 v64, v80, v96
	v_mul_f32_e32 v65, v81, v96
	v_mul_f32_e32 v66, v82, v96
	v_mul_f32_e32 v67, v83, v96
	v_mul_f32_e32 v68, v84, v96
	v_mul_f32_e32 v69, v85, v96
	v_mul_f32_e32 v70, v86, v96
	v_mul_f32_e32 v71, v87, v96
	v_mul_f32_e32 v72, v88, v96
	v_mul_f32_e32 v73, v89, v96
	v_mul_f32_e32 v74, v90, v96
	v_mul_f32_e32 v75, v91, v96
	v_mul_f32_e32 v76, v92, v96
	v_mul_f32_e32 v77, v93, v96
	v_mul_f32_e32 v78, v94, v96
	v_mul_f32_e32 v79, v95, v96
	v_mul_f32_e32 v64, v128, v64
	v_mul_f32_e32 v65, v129, v65
	v_mul_f32_e32 v66, v130, v66
	v_mul_f32_e32 v67, v131, v67
	v_mul_f32_e32 v68, v132, v68
	v_mul_f32_e32 v69, v133, v69
	v_mul_f32_e32 v70, v134, v70
	v_mul_f32_e32 v71, v135, v71
	v_mul_f32_e32 v72, v136, v72
	v_mul_f32_e32 v73, v137, v73
	v_mul_f32_e32 v74, v138, v74
	v_mul_f32_e32 v75, v139, v75
	v_mul_f32_e32 v76, v140, v76
	v_mul_f32_e32 v77, v141, v77
	v_mul_f32_e32 v78, v142, v78
	v_mul_f32_e32 v79, v143, v79
	v_cvt_pk_bf16_f32 v148, v64, v65
	v_cvt_pk_bf16_f32 v149, v66, v67
	global_store_dwordx2 v145, v[148:149], s[42:43] offset:0
	v_cvt_pk_bf16_f32 v150, v68, v69
	v_cvt_pk_bf16_f32 v151, v70, v71
	global_store_dwordx2 v145, v[150:151], s[42:43] offset:512
	v_cvt_pk_bf16_f32 v152, v72, v73
	v_cvt_pk_bf16_f32 v153, v74, v75
	global_store_dwordx2 v145, v[152:153], s[42:43] offset:1024
	v_cvt_pk_bf16_f32 v154, v76, v77
	v_cvt_pk_bf16_f32 v155, v78, v79
	global_store_dwordx2 v145, v[154:155], s[42:43] offset:1536
	s_add_u32 s40, s40, 0x1000
	s_addc_u32 s41, s41, 0
	s_add_u32 s42, s42, 0x800
	s_addc_u32 s43, s43, 0
	s_waitcnt vmcnt(24)
	v_mul_f32_e32 v96, v1, v1
	v_mul_f32_e32 v98, v3, v3
	v_fmac_f32_e32 v96, v0, v0
	v_fmac_f32_e32 v98, v2, v2
	v_add_f32_e32 v96, v96, v98
	v_mul_f32_e32 v97, v5, v5
	v_mul_f32_e32 v98, v7, v7
	v_fmac_f32_e32 v97, v4, v4
	v_fmac_f32_e32 v98, v6, v6
	v_add_f32_e32 v97, v97, v98
	v_add_f32_e32 v96, v97, v96
	v_mul_f32_e32 v97, v9, v9
	v_mul_f32_e32 v98, v11, v11
	v_fmac_f32_e32 v97, v8, v8
	v_fmac_f32_e32 v98, v10, v10
	v_add_f32_e32 v97, v97, v98
	v_add_f32_e32 v96, v97, v96
	v_mul_f32_e32 v97, v13, v13
	v_mul_f32_e32 v98, v15, v15
	v_fmac_f32_e32 v97, v12, v12
	v_fmac_f32_e32 v98, v14, v14
	v_add_f32_e32 v97, v97, v98
	v_add_f32_e32 v96, v97, v96
	s_nop 1
	v_add_f32_dpp v96, v96, v96 quad_perm:[1,0,3,2] row_mask:0xf bank_mask:0xf bound_ctrl:1
	s_nop 1
	v_add_f32_dpp v96, v96, v96 quad_perm:[2,3,0,1] row_mask:0xf bank_mask:0xf bound_ctrl:1
	s_nop 1
	v_add_f32_dpp v96, v96, v96 row_half_mirror row_mask:0xf bank_mask:0xf bound_ctrl:1
	s_nop 1
	v_add_f32_dpp v96, v96, v96 row_mirror row_mask:0xf bank_mask:0xf bound_ctrl:1
	v_mov_b32_e32 v97, v96
	s_nop 1
	v_permlane16_swap_b32_e32 v96, v97
	v_add_f32_e32 v96, v96, v97
	v_mov_b32_e32 v97, v96
	s_nop 1
	v_permlane32_swap_b32_e32 v96, v97
	v_add_f32_e32 v96, v96, v97
	v_fmamk_f32 v96, v96, 0x3a800000, v146
	v_mul_f32_e32 v97, 0x4f800000, v96
	v_cmp_gt_f32_e32 vcc, s33, v96
	s_nop 1
	v_cndmask_b32_e32 v96, v96, v97, vcc
	v_sqrt_f32_e32 v97, v96
	s_nop 0
	v_add_u32_e32 v98, -1, v97
	v_fma_f32 v99, -v98, v97, v96
	v_cmp_ge_f32_e64 s[4:5], 0, v99
	v_add_u32_e32 v99, 1, v97
	s_nop 0
	v_cndmask_b32_e64 v98, v97, v98, s[4:5]
	v_fma_f32 v97, -v99, v97, v96
	v_cmp_lt_f32_e64 s[4:5], 0, v97
	s_nop 1
	v_cndmask_b32_e64 v97, v98, v99, s[4:5]
	v_mul_f32_e32 v98, 0x37800000, v97
	v_cndmask_b32_e32 v97, v97, v98, vcc
	v_cmp_class_f32_e32 vcc, v96, v147
	s_nop 1
	v_cndmask_b32_e32 v96, v97, v96, vcc
	v_div_scale_f32 v97, s[4:5], v96, v96, 0.5
	v_rcp_f32_e32 v98, v97
	s_nop 0
	v_fma_f32 v99, -v97, v98, 1.0
	v_fmac_f32_e32 v98, v99, v98
	v_div_scale_f32 v99, vcc, 0.5, v96, 0.5
	v_mul_f32_e32 v100, v99, v98
	v_fma_f32 v101, -v97, v100, v99
	v_fmac_f32_e32 v100, v101, v98
	v_fma_f32 v97, -v97, v100, v99
	v_div_fmas_f32 v97, v97, v98, v100
	v_div_fixup_f32 v96, v97, v96, 0.5
	v_mul_f32_e32 v0, v0, v96
	v_mul_f32_e32 v1, v1, v96
	v_mul_f32_e32 v2, v2, v96
	v_mul_f32_e32 v3, v3, v96
	v_mul_f32_e32 v4, v4, v96
	v_mul_f32_e32 v5, v5, v96
	v_mul_f32_e32 v6, v6, v96
	v_mul_f32_e32 v7, v7, v96
	v_mul_f32_e32 v8, v8, v96
	v_mul_f32_e32 v9, v9, v96
	v_mul_f32_e32 v10, v10, v96
	v_mul_f32_e32 v11, v11, v96
	v_mul_f32_e32 v12, v12, v96
	v_mul_f32_e32 v13, v13, v96
	v_mul_f32_e32 v14, v14, v96
	v_mul_f32_e32 v15, v15, v96
	v_fmac_f32_e32 v16, v112, v0
	v_fmac_f32_e32 v17, v113, v1
	v_fmac_f32_e32 v18, v114, v2
	v_fmac_f32_e32 v19, v115, v3
	v_fmac_f32_e32 v20, v116, v4
	v_fmac_f32_e32 v21, v117, v5
	v_fmac_f32_e32 v22, v118, v6
	v_fmac_f32_e32 v23, v119, v7
	v_fmac_f32_e32 v24, v120, v8
	v_fmac_f32_e32 v25, v121, v9
	v_fmac_f32_e32 v26, v122, v10
	v_fmac_f32_e32 v27, v123, v11
	v_fmac_f32_e32 v28, v124, v12
	v_fmac_f32_e32 v29, v125, v13
	v_fmac_f32_e32 v30, v126, v14
	v_fmac_f32_e32 v31, v127, v15
	global_store_dwordx4 v144, v[16:19], s[40:41] offset:0
	global_store_dwordx4 v144, v[20:23], s[40:41] offset:1024
	global_store_dwordx4 v144, v[24:27], s[40:41] offset:2048
	global_store_dwordx4 v144, v[28:31], s[40:41] offset:3072
	v_mul_f32_e32 v96, v17, v17
	v_mul_f32_e32 v98, v19, v19
	v_fmac_f32_e32 v96, v16, v16
	v_fmac_f32_e32 v98, v18, v18
	v_add_f32_e32 v96, v96, v98
	v_mul_f32_e32 v97, v21, v21
	v_mul_f32_e32 v98, v23, v23
	v_fmac_f32_e32 v97, v20, v20
	v_fmac_f32_e32 v98, v22, v22
	v_add_f32_e32 v97, v97, v98
	v_add_f32_e32 v96, v97, v96
	v_mul_f32_e32 v97, v25, v25
	v_mul_f32_e32 v98, v27, v27
	v_fmac_f32_e32 v97, v24, v24
	v_fmac_f32_e32 v98, v26, v26
	v_add_f32_e32 v97, v97, v98
	v_add_f32_e32 v96, v97, v96
	v_mul_f32_e32 v97, v29, v29
	v_mul_f32_e32 v98, v31, v31
	v_fmac_f32_e32 v97, v28, v28
; __device__ __forceinline__ unsigned pk2(float lo, float hi) { f32x2 v = {lo, hi}; bf16x2_t b = __builtin_convertvector(v, bf16x2_t); return __builtin_bit_cast(unsigned, b); }
; __device__ __forceinline__ void phase_rowpass(const Ctx& p, const float* F, int base_is_x, float alpha, const float* gpost, const float* gnext, bf16_t* XN, const float* PART, int nsplit) {
;     ...
;         float s = 0.f;
; #pragma unroll
;         for (int j = 0; j < 4; ++j) s += (f[j].x * f[j].x + f[j].y * f[j].y) + (f[j].z * f[j].z + f[j].w * f[j].w);
;         const float rs = alpha / sqrtf(wave_sum_fast(s) * (1.f / DM) + EPS);
;     ...
;             const float r2 = 1.f / sqrtf(wave_sum_fast(s2) * (1.f / DM) + EPS);
;             u32x2* o8 = (u32x2*)(XN + (size_t)m * DM) + lane;
; #pragma unroll
;             for (int j = 0; j < 4; ++j) { u32x2 w; w.x = pk2(b[j].x * r2 * gn[j].x, b[j].y * r2 * gn[j].y); w.y = pk2(b[j].z * r2 * gn[j].z, b[j].w * r2 * gn[j].w); o8[64 * j] = w; }
	v_fmac_f32_e32 v98, v30, v30
	v_add_f32_e32 v97, v97, v98
	v_add_f32_e32 v96, v97, v96
	s_nop 1
	v_add_f32_dpp v96, v96, v96 quad_perm:[1,0,3,2] row_mask:0xf bank_mask:0xf bound_ctrl:1
	s_nop 1
	v_add_f32_dpp v96, v96, v96 quad_perm:[2,3,0,1] row_mask:0xf bank_mask:0xf bound_ctrl:1
	s_nop 1
	v_add_f32_dpp v96, v96, v96 row_half_mirror row_mask:0xf bank_mask:0xf bound_ctrl:1
	s_nop 1
	v_add_f32_dpp v96, v96, v96 row_mirror row_mask:0xf bank_mask:0xf bound_ctrl:1
	v_mov_b32_e32 v97, v96
	s_nop 1
	v_permlane16_swap_b32_e32 v96, v97
	v_add_f32_e32 v96, v96, v97
	v_mov_b32_e32 v97, v96
	s_nop 1
	v_permlane32_swap_b32_e32 v96, v97
	v_add_f32_e32 v96, v96, v97
	v_fmamk_f32 v96, v96, 0x3a800000, v146
	v_mul_f32_e32 v97, 0x4f800000, v96
	v_cmp_gt_f32_e32 vcc, s33, v96
	s_nop 1
	v_cndmask_b32_e32 v96, v96, v97, vcc
	v_sqrt_f32_e32 v97, v96
	s_nop 0
	v_add_u32_e32 v98, -1, v97
	v_fma_f32 v99, -v98, v97, v96
	v_cmp_ge_f32_e64 s[4:5], 0, v99
	v_add_u32_e32 v99, 1, v97
	s_nop 0
	v_cndmask_b32_e64 v98, v97, v98, s[4:5]
	v_fma_f32 v97, -v99, v97, v96
	v_cmp_lt_f32_e64 s[4:5], 0, v97
	s_nop 1
	v_cndmask_b32_e64 v97, v98, v99, s[4:5]
	v_mul_f32_e32 v98, 0x37800000, v97
	v_cndmask_b32_e32 v97, v97, v98, vcc
	v_cmp_class_f32_e32 vcc, v96, v147
	s_nop 1
	v_cndmask_b32_e32 v96, v97, v96, vcc
	v_div_scale_f32 v97, s[4:5], v96, v96, 1.0
	v_rcp_f32_e32 v98, v97
	s_nop 0
	v_fma_f32 v99, -v97, v98, 1.0
	v_fmac_f32_e32 v98, v99, v98
	v_div_scale_f32 v99, vcc, 1.0, v96, 1.0
	v_mul_f32_e32 v100, v99, v98
	v_fma_f32 v101, -v97, v100, v99
	v_fmac_f32_e32 v100, v101, v98
	v_fma_f32 v97, -v97, v100, v99
	v_div_fmas_f32 v97, v97, v98, v100
	v_div_fixup_f32 v96, v97, v96, 1.0
	v_mul_f32_e32 v0, v16, v96
	v_mul_f32_e32 v1, v17, v96
	v_mul_f32_e32 v2, v18, v96
	v_mul_f32_e32 v3, v19, v96
	v_mul_f32_e32 v4, v20, v96
	v_mul_f32_e32 v5, v21, v96
	v_mul_f32_e32 v6, v22, v96
	v_mul_f32_e32 v7, v23, v96
	v_mul_f32_e32 v8, v24, v96
	v_mul_f32_e32 v9, v25, v96
	v_mul_f32_e32 v10, v26, v96
	v_mul_f32_e32 v11, v27, v96
	v_mul_f32_e32 v12, v28, v96
	v_mul_f32_e32 v13, v29, v96
	v_mul_f32_e32 v14, v30, v96
	v_mul_f32_e32 v15, v31, v96
	v_mul_f32_e32 v0, v128, v0
	v_mul_f32_e32 v1, v129, v1
	v_mul_f32_e32 v2, v130, v2
	v_mul_f32_e32 v3, v131, v3
	v_mul_f32_e32 v4, v132, v4
	v_mul_f32_e32 v5, v133, v5
	v_mul_f32_e32 v6, v134, v6
	v_mul_f32_e32 v7, v135, v7
	v_mul_f32_e32 v8, v136, v8
	v_mul_f32_e32 v9, v137, v9
	v_mul_f32_e32 v10, v138, v10
	v_mul_f32_e32 v11, v139, v11
	v_mul_f32_e32 v12, v140, v12
	v_mul_f32_e32 v13, v141, v13
	v_mul_f32_e32 v14, v142, v14
	v_mul_f32_e32 v15, v143, v15
	v_cvt_pk_bf16_f32 v148, v0, v1
	v_cvt_pk_bf16_f32 v149, v2, v3
	global_store_dwordx2 v145, v[148:149], s[42:43] offset:0
	v_cvt_pk_bf16_f32 v150, v4, v5
	v_cvt_pk_bf16_f32 v151, v6, v7
	global_store_dwordx2 v145, v[150:151], s[42:43] offset:512
	v_cvt_pk_bf16_f32 v152, v8, v9
	v_cvt_pk_bf16_f32 v153, v10, v11
	global_store_dwordx2 v145, v[152:153], s[42:43] offset:1024
	v_cvt_pk_bf16_f32 v154, v12, v13
	v_cvt_pk_bf16_f32 v155, v14, v15
	global_store_dwordx2 v145, v[154:155], s[42:43] offset:1536
	s_add_u32 s40, s40, 0x1000
	s_addc_u32 s41, s41, 0
	s_add_u32 s42, s42, 0x800
	s_addc_u32 s43, s43, 0
	s_waitcnt vmcnt(16)
	v_mul_f32_e32 v96, v33, v33
	v_mul_f32_e32 v98, v35, v35
	v_fmac_f32_e32 v96, v32, v32
	v_fmac_f32_e32 v98, v34, v34
	v_add_f32_e32 v96, v96, v98
	v_mul_f32_e32 v97, v37, v37
	v_mul_f32_e32 v98, v39, v39
	v_fmac_f32_e32 v97, v36, v36
	v_fmac_f32_e32 v98, v38, v38
	v_add_f32_e32 v97, v97, v98
	v_add_f32_e32 v96, v97, v96
	v_mul_f32_e32 v97, v41, v41
	v_mul_f32_e32 v98, v43, v43
	v_fmac_f32_e32 v97, v40, v40
	v_fmac_f32_e32 v98, v42, v42
	v_add_f32_e32 v97, v97, v98
	v_add_f32_e32 v96, v97, v96
	v_mul_f32_e32 v97, v45, v45
	v_mul_f32_e32 v98, v47, v47
	v_fmac_f32_e32 v97, v44, v44
	v_fmac_f32_e32 v98, v46, v46
	v_add_f32_e32 v97, v97, v98
	v_add_f32_e32 v96, v97, v96
	s_nop 1
	v_add_f32_dpp v96, v96, v96 quad_perm:[1,0,3,2] row_mask:0xf bank_mask:0xf bound_ctrl:1
	s_nop 1
	v_add_f32_dpp v96, v96, v96 quad_perm:[2,3,0,1] row_mask:0xf bank_mask:0xf bound_ctrl:1
	s_nop 1
	v_add_f32_dpp v96, v96, v96 row_half_mirror row_mask:0xf bank_mask:0xf bound_ctrl:1
	s_nop 1
	v_add_f32_dpp v96, v96, v96 row_mirror row_mask:0xf bank_mask:0xf bound_ctrl:1
	v_mov_b32_e32 v97, v96
	s_nop 1
	v_permlane16_swap_b32_e32 v96, v97
	v_add_f32_e32 v96, v96, v97
	v_mov_b32_e32 v97, v96
	s_nop 1
	v_permlane32_swap_b32_e32 v96, v97
	v_add_f32_e32 v96, v96, v97
	v_fmamk_f32 v96, v96, 0x3a800000, v146
	v_mul_f32_e32 v97, 0x4f800000, v96
	v_cmp_gt_f32_e32 vcc, s33, v96
	s_nop 1
	v_cndmask_b32_e32 v96, v96, v97, vcc
	v_sqrt_f32_e32 v97, v96
	s_nop 0
	v_add_u32_e32 v98, -1, v97
	v_fma_f32 v99, -v98, v97, v96
	v_cmp_ge_f32_e64 s[4:5], 0, v99
	v_add_u32_e32 v99, 1, v97
	s_nop 0
	v_cndmask_b32_e64 v98, v97, v98, s[4:5]
	v_fma_f32 v97, -v99, v97, v96
	v_cmp_lt_f32_e64 s[4:5], 0, v97
	s_nop 1
	v_cndmask_b32_e64 v97, v98, v99, s[4:5]
	v_mul_f32_e32 v98, 0x37800000, v97
	v_cndmask_b32_e32 v97, v97, v98, vcc
	v_cmp_class_f32_e32 vcc, v96, v147
	s_nop 1
	v_cndmask_b32_e32 v96, v97, v96, vcc
	v_div_scale_f32 v97, s[4:5], v96, v96, 0.5
	v_rcp_f32_e32 v98, v97
	s_nop 0
	v_fma_f32 v99, -v97, v98, 1.0
	v_fmac_f32_e32 v98, v99, v98
	v_div_scale_f32 v99, vcc, 0.5, v96, 0.5
	v_mul_f32_e32 v100, v99, v98
	v_fma_f32 v101, -v97, v100, v99
	v_fmac_f32_e32 v100, v101, v98
	v_fma_f32 v97, -v97, v100, v99
	v_div_fmas_f32 v97, v97, v98, v100
	v_div_fixup_f32 v96, v97, v96, 0.5
	v_mul_f32_e32 v32, v32, v96
	v_mul_f32_e32 v33, v33, v96
	v_mul_f32_e32 v34, v34, v96
	v_mul_f32_e32 v35, v35, v96
	v_mul_f32_e32 v36, v36, v96
	v_mul_f32_e32 v37, v37, v96
; __device__ __forceinline__ unsigned pk2(float lo, float hi) { f32x2 v = {lo, hi}; bf16x2_t b = __builtin_convertvector(v, bf16x2_t); return __builtin_bit_cast(unsigned, b); }
; __device__ __forceinline__ void phase_rowpass(const Ctx& p, const float* F, int base_is_x, float alpha, const float* gpost, const float* gnext, bf16_t* XN, const float* PART, int nsplit) {
;     ...
;         const float rs = alpha / sqrtf(wave_sum_fast(s) * (1.f / DM) + EPS);
;         float s2 = 0.f;
; #pragma unroll
;         for (int j = 0; j < 4; ++j) { b[j] = b[j] + f[j] * rs * gp[j]; s2 += (b[j].x * b[j].x + b[j].y * b[j].y) + (b[j].z * b[j].z + b[j].w * b[j].w);
;             ((f32x4*)(H + (size_t)m * DM))[lane + 64 * j] = b[j]; }
;         if (gnext) {
;             const float r2 = 1.f / sqrtf(wave_sum_fast(s2) * (1.f / DM) + EPS);
;             u32x2* o8 = (u32x2*)(XN + (size_t)m * DM) + lane;
; #pragma unroll
;             for (int j = 0; j < 4; ++j) { u32x2 w; w.x = pk2(b[j].x * r2 * gn[j].x, b[j].y * r2 * gn[j].y); w.y = pk2(b[j].z * r2 * gn[j].z, b[j].w * r2 * gn[j].w); o8[64 * j] = w; }
	v_mul_f32_e32 v38, v38, v96
	v_mul_f32_e32 v39, v39, v96
	v_mul_f32_e32 v40, v40, v96
	v_mul_f32_e32 v41, v41, v96
	v_mul_f32_e32 v42, v42, v96
	v_mul_f32_e32 v43, v43, v96
	v_mul_f32_e32 v44, v44, v96
	v_mul_f32_e32 v45, v45, v96
	v_mul_f32_e32 v46, v46, v96
	v_mul_f32_e32 v47, v47, v96
	v_fmac_f32_e32 v48, v112, v32
	v_fmac_f32_e32 v49, v113, v33
	v_fmac_f32_e32 v50, v114, v34
	v_fmac_f32_e32 v51, v115, v35
	v_fmac_f32_e32 v52, v116, v36
	v_fmac_f32_e32 v53, v117, v37
	v_fmac_f32_e32 v54, v118, v38
	v_fmac_f32_e32 v55, v119, v39
	v_fmac_f32_e32 v56, v120, v40
	v_fmac_f32_e32 v57, v121, v41
	v_fmac_f32_e32 v58, v122, v42
	v_fmac_f32_e32 v59, v123, v43
	v_fmac_f32_e32 v60, v124, v44
	v_fmac_f32_e32 v61, v125, v45
	v_fmac_f32_e32 v62, v126, v46
	v_fmac_f32_e32 v63, v127, v47
	global_store_dwordx4 v144, v[48:51], s[40:41] offset:0
	global_store_dwordx4 v144, v[52:55], s[40:41] offset:1024
	global_store_dwordx4 v144, v[56:59], s[40:41] offset:2048
	global_store_dwordx4 v144, v[60:63], s[40:41] offset:3072
	v_mul_f32_e32 v96, v49, v49
	v_mul_f32_e32 v98, v51, v51
	v_fmac_f32_e32 v96, v48, v48
	v_fmac_f32_e32 v98, v50, v50
	v_add_f32_e32 v96, v96, v98
	v_mul_f32_e32 v97, v53, v53
	v_mul_f32_e32 v98, v55, v55
	v_fmac_f32_e32 v97, v52, v52
	v_fmac_f32_e32 v98, v54, v54
	v_add_f32_e32 v97, v97, v98
	v_add_f32_e32 v96, v97, v96
	v_mul_f32_e32 v97, v57, v57
	v_mul_f32_e32 v98, v59, v59
	v_fmac_f32_e32 v97, v56, v56
	v_fmac_f32_e32 v98, v58, v58
	v_add_f32_e32 v97, v97, v98
	v_add_f32_e32 v96, v97, v96
	v_mul_f32_e32 v97, v61, v61
	v_mul_f32_e32 v98, v63, v63
	v_fmac_f32_e32 v97, v60, v60
	v_fmac_f32_e32 v98, v62, v62
	v_add_f32_e32 v97, v97, v98
	v_add_f32_e32 v96, v97, v96
	s_nop 1
	v_add_f32_dpp v96, v96, v96 quad_perm:[1,0,3,2] row_mask:0xf bank_mask:0xf bound_ctrl:1
	s_nop 1
	v_add_f32_dpp v96, v96, v96 quad_perm:[2,3,0,1] row_mask:0xf bank_mask:0xf bound_ctrl:1
	s_nop 1
	v_add_f32_dpp v96, v96, v96 row_half_mirror row_mask:0xf bank_mask:0xf bound_ctrl:1
	s_nop 1
	v_add_f32_dpp v96, v96, v96 row_mirror row_mask:0xf bank_mask:0xf bound_ctrl:1
	v_mov_b32_e32 v97, v96
	s_nop 1
	v_permlane16_swap_b32_e32 v96, v97
	v_add_f32_e32 v96, v96, v97
	v_mov_b32_e32 v97, v96
	s_nop 1
	v_permlane32_swap_b32_e32 v96, v97
	v_add_f32_e32 v96, v96, v97
	v_fmamk_f32 v96, v96, 0x3a800000, v146
	v_mul_f32_e32 v97, 0x4f800000, v96
	v_cmp_gt_f32_e32 vcc, s33, v96
	s_nop 1
	v_cndmask_b32_e32 v96, v96, v97, vcc
	v_sqrt_f32_e32 v97, v96
	s_nop 0
	v_add_u32_e32 v98, -1, v97
	v_fma_f32 v99, -v98, v97, v96
	v_cmp_ge_f32_e64 s[4:5], 0, v99
	v_add_u32_e32 v99, 1, v97
	s_nop 0
	v_cndmask_b32_e64 v98, v97, v98, s[4:5]
	v_fma_f32 v97, -v99, v97, v96
	v_cmp_lt_f32_e64 s[4:5], 0, v97
	s_nop 1
	v_cndmask_b32_e64 v97, v98, v99, s[4:5]
	v_mul_f32_e32 v98, 0x37800000, v97
	v_cndmask_b32_e32 v97, v97, v98, vcc
	v_cmp_class_f32_e32 vcc, v96, v147
	s_nop 1
	v_cndmask_b32_e32 v96, v97, v96, vcc
	v_div_scale_f32 v97, s[4:5], v96, v96, 1.0
	v_rcp_f32_e32 v98, v97
	s_nop 0
	v_fma_f32 v99, -v97, v98, 1.0
	v_fmac_f32_e32 v98, v99, v98
	v_div_scale_f32 v99, vcc, 1.0, v96, 1.0
	v_mul_f32_e32 v100, v99, v98
	v_fma_f32 v101, -v97, v100, v99
	v_fmac_f32_e32 v100, v101, v98
	v_fma_f32 v97, -v97, v100, v99
	v_div_fmas_f32 v97, v97, v98, v100
	v_div_fixup_f32 v96, v97, v96, 1.0
	v_mul_f32_e32 v32, v48, v96
	v_mul_f32_e32 v33, v49, v96
	v_mul_f32_e32 v34, v50, v96
	v_mul_f32_e32 v35, v51, v96
	v_mul_f32_e32 v36, v52, v96
	v_mul_f32_e32 v37, v53, v96
	v_mul_f32_e32 v38, v54, v96
	v_mul_f32_e32 v39, v55, v96
	v_mul_f32_e32 v40, v56, v96
	v_mul_f32_e32 v41, v57, v96
	v_mul_f32_e32 v42, v58, v96
	v_mul_f32_e32 v43, v59, v96
	v_mul_f32_e32 v44, v60, v96
	v_mul_f32_e32 v45, v61, v96
	v_mul_f32_e32 v46, v62, v96
	v_mul_f32_e32 v47, v63, v96
	v_mul_f32_e32 v32, v128, v32
	v_mul_f32_e32 v33, v129, v33
	v_mul_f32_e32 v34, v130, v34
	v_mul_f32_e32 v35, v131, v35
	v_mul_f32_e32 v36, v132, v36
	v_mul_f32_e32 v37, v133, v37
	v_mul_f32_e32 v38, v134, v38
	v_mul_f32_e32 v39, v135, v39
	v_mul_f32_e32 v40, v136, v40
	v_mul_f32_e32 v41, v137, v41
	v_mul_f32_e32 v42, v138, v42
	v_mul_f32_e32 v43, v139, v43
	v_mul_f32_e32 v44, v140, v44
	v_mul_f32_e32 v45, v141, v45
	v_mul_f32_e32 v46, v142, v46
	v_mul_f32_e32 v47, v143, v47
	v_cvt_pk_bf16_f32 v148, v32, v33
	v_cvt_pk_bf16_f32 v149, v34, v35
	global_store_dwordx2 v145, v[148:149], s[42:43] offset:0
	v_cvt_pk_bf16_f32 v150, v36, v37
	v_cvt_pk_bf16_f32 v151, v38, v39
	global_store_dwordx2 v145, v[150:151], s[42:43] offset:512
	v_cvt_pk_bf16_f32 v152, v40, v41
	v_cvt_pk_bf16_f32 v153, v42, v43
	global_store_dwordx2 v145, v[152:153], s[42:43] offset:1024
	v_cvt_pk_bf16_f32 v154, v44, v45
	v_cvt_pk_bf16_f32 v155, v46, v47
	global_store_dwordx2 v145, v[154:155], s[42:43] offset:1536
	s_add_u32 s40, s40, 0x1000
	s_addc_u32 s41, s41, 0
	s_add_u32 s42, s42, 0x800
	s_addc_u32 s43, s43, 0
	s_sub_u32 s21, s28, 44
	s_cmp_lt_u32 s21, 16
	s_cbranch_scc0 .Lfrp3_end
; __device__ __forceinline__ const float* xrow_ptr(const Ctx& p, int row) { return row < MPR ? p.in(0) + (size_t)row * DM : p.in(1) + (size_t)(row - MPR) * DM; }
; __device__ __forceinline__ void phase_rowpass(const Ctx& p, const float* F, int base_is_x, float alpha, const float* gpost, const float* gnext, bf16_t* XN, const float* PART, int nsplit) {
;     ...
;     auto loadrow = [&](int m, f32x4 (&f)[4], f32x4 (&b)[4]) {
;         const f32x4* fr = (const f32x4*)(F + (size_t)m * DM) + lane;
;         const f32x4* br = (const f32x4*)(base_is_x ? xrow_ptr(p, m) : H + (size_t)m * DM) + lane;
; #pragma unroll
;         for (int j = 0; j < 4; ++j) { b[j] = br[64 * j];
;             if (m < MPR) f[j] = fr[64 * j];
;             else { f[j] = (f32x4){0.f, 0.f, 0.f, 0.f};
;                 for (int ks = 0; ks < nsplit; ++ks) f[j] = f[j] + ((const f32x4*)(PART + ((size_t)ks * 128 + (m - MPR)) * DM))[lane + 64 * j]; } }
	s_waitcnt vmcnt(0)
	s_lshl_b32 s19, s21, 3
	s_add_i32 s19, s19, s20
	s_add_i32 s23, s19, 0x4000
	s_lshl_b32 s21, s23, 12
	s_add_u32 s40, s8, s21
	s_addc_u32 s41, s9, 0
	s_lshl_b32 s22, s23, 11
	s_add_u32 s42, s30, s22
	s_addc_u32 s43, s31, 0
	s_add_u32 s42, s42, 0x3200000
	s_addc_u32 s43, s43, 0
	s_lshl_b32 s21, s19, 12
	s_add_u32 s24, s30, s21
	s_addc_u32 s25, s31, 0
	s_add_u32 s24, s24, 0xf000000
	s_addc_u32 s25, s25, 0
	s_add_u32 s26, s16, s21
	s_addc_u32 s27, s17, 0
	global_load_dwordx4 v[200:203], v144, s[26:27] offset:0
	global_load_dwordx4 v[204:207], v144, s[26:27] offset:1024
	global_load_dwordx4 v[208:211], v144, s[26:27] offset:2048
	global_load_dwordx4 v[212:215], v144, s[26:27] offset:3072
	s_mov_b32 s34, s24
	s_mov_b32 s35, s25
	global_load_dwordx4 v[0:3], v144, s[34:35] offset:0
	global_load_dwordx4 v[44:47], v144, s[34:35] offset:1024
	s_add_u32 s34, s34, 0x80000
	s_addc_u32 s35, s35, 0
	global_load_dwordx4 v[4:7], v144, s[34:35] offset:0
	global_load_dwordx4 v[48:51], v144, s[34:35] offset:1024
	s_add_u32 s34, s34, 0x80000
	s_addc_u32 s35, s35, 0
	global_load_dwordx4 v[8:11], v144, s[34:35] offset:0
	global_load_dwordx4 v[52:55], v144, s[34:35] offset:1024
	s_add_u32 s34, s34, 0x80000
	s_addc_u32 s35, s35, 0
	global_load_dwordx4 v[12:15], v144, s[34:35] offset:0
	global_load_dwordx4 v[56:59], v144, s[34:35] offset:1024
	s_add_u32 s34, s34, 0x80000
	s_addc_u32 s35, s35, 0
	global_load_dwordx4 v[16:19], v144, s[34:35] offset:0
	global_load_dwordx4 v[60:63], v144, s[34:35] offset:1024
	s_add_u32 s34, s34, 0x80000
	s_addc_u32 s35, s35, 0
	global_load_dwordx4 v[20:23], v144, s[34:35] offset:0
	global_load_dwordx4 v[64:67], v144, s[34:35] offset:1024
	s_add_u32 s34, s34, 0x80000
	s_addc_u32 s35, s35, 0
	global_load_dwordx4 v[24:27], v144, s[34:35] offset:0
	global_load_dwordx4 v[68:71], v144, s[34:35] offset:1024
	s_add_u32 s34, s34, 0x80000
	s_addc_u32 s35, s35, 0
	global_load_dwordx4 v[28:31], v144, s[34:35] offset:0
	global_load_dwordx4 v[72:75], v144, s[34:35] offset:1024
	s_add_u32 s34, s34, 0x80000
	s_addc_u32 s35, s35, 0
	global_load_dwordx4 v[32:35], v144, s[34:35] offset:0
	global_load_dwordx4 v[76:79], v144, s[34:35] offset:1024
	s_add_u32 s34, s34, 0x80000
	s_addc_u32 s35, s35, 0
	global_load_dwordx4 v[36:39], v144, s[34:35] offset:0
	global_load_dwordx4 v[80:83], v144, s[34:35] offset:1024
	s_add_u32 s34, s34, 0x80000
	s_addc_u32 s35, s35, 0
	global_load_dwordx4 v[40:43], v144, s[34:35] offset:0
	global_load_dwordx4 v[84:87], v144, s[34:35] offset:1024
	s_waitcnt vmcnt(21)
	v_mov_b32_e32 v184, v0
	v_mov_b32_e32 v185, v1
	v_mov_b32_e32 v186, v2
	v_mov_b32_e32 v187, v3
	s_waitcnt vmcnt(19)
	v_add_f32_e32 v184, v184, v4
	v_add_f32_e32 v185, v185, v5
	v_add_f32_e32 v186, v186, v6
	v_add_f32_e32 v187, v187, v7
	s_waitcnt vmcnt(17)
	v_add_f32_e32 v184, v184, v8
	v_add_f32_e32 v185, v185, v9
	v_add_f32_e32 v186, v186, v10
	v_add_f32_e32 v187, v187, v11
	s_waitcnt vmcnt(15)
	v_add_f32_e32 v184, v184, v12
	v_add_f32_e32 v185, v185, v13
	v_add_f32_e32 v186, v186, v14
	v_add_f32_e32 v187, v187, v15
	s_waitcnt vmcnt(13)
	v_add_f32_e32 v184, v184, v16
	v_add_f32_e32 v185, v185, v17
	v_add_f32_e32 v186, v186, v18
	v_add_f32_e32 v187, v187, v19
	s_waitcnt vmcnt(11)
	v_add_f32_e32 v184, v184, v20
	v_add_f32_e32 v185, v185, v21
	v_add_f32_e32 v186, v186, v22
	v_add_f32_e32 v187, v187, v23
	s_waitcnt vmcnt(9)
	v_add_f32_e32 v184, v184, v24
	v_add_f32_e32 v185, v185, v25
	v_add_f32_e32 v186, v186, v26
	v_add_f32_e32 v187, v187, v27
	s_waitcnt vmcnt(7)
	v_add_f32_e32 v184, v184, v28
	v_add_f32_e32 v185, v185, v29
	v_add_f32_e32 v186, v186, v30
	v_add_f32_e32 v187, v187, v31
	s_waitcnt vmcnt(5)
	v_add_f32_e32 v184, v184, v32
	v_add_f32_e32 v185, v185, v33
	v_add_f32_e32 v186, v186, v34
	v_add_f32_e32 v187, v187, v35
	s_waitcnt vmcnt(3)
	v_add_f32_e32 v184, v184, v36
	v_add_f32_e32 v185, v185, v37
	v_add_f32_e32 v186, v186, v38
	v_add_f32_e32 v187, v187, v39
	s_waitcnt vmcnt(1)
	v_add_f32_e32 v184, v184, v40
	v_add_f32_e32 v185, v185, v41
	v_add_f32_e32 v186, v186, v42
	v_add_f32_e32 v187, v187, v43
	s_waitcnt vmcnt(20)
	v_mov_b32_e32 v188, v44
	v_mov_b32_e32 v189, v45
	v_mov_b32_e32 v190, v46
	v_mov_b32_e32 v191, v47
	s_waitcnt vmcnt(18)
	v_add_f32_e32 v188, v188, v48
	v_add_f32_e32 v189, v189, v49
	v_add_f32_e32 v190, v190, v50
	v_add_f32_e32 v191, v191, v51
	s_waitcnt vmcnt(16)
	v_add_f32_e32 v188, v188, v52
	v_add_f32_e32 v189, v189, v53
	v_add_f32_e32 v190, v190, v54
	v_add_f32_e32 v191, v191, v55
	s_waitcnt vmcnt(14)
	v_add_f32_e32 v188, v188, v56
	v_add_f32_e32 v189, v189, v57
	v_add_f32_e32 v190, v190, v58
	v_add_f32_e32 v191, v191, v59
	s_waitcnt vmcnt(12)
	v_add_f32_e32 v188, v188, v60
	v_add_f32_e32 v189, v189, v61
	v_add_f32_e32 v190, v190, v62
	v_add_f32_e32 v191, v191, v63
	s_waitcnt vmcnt(10)
	v_add_f32_e32 v188, v188, v64
	v_add_f32_e32 v189, v189, v65
	v_add_f32_e32 v190, v190, v66
	v_add_f32_e32 v191, v191, v67
	s_waitcnt vmcnt(8)
	v_add_f32_e32 v188, v188, v68
	v_add_f32_e32 v189, v189, v69
	v_add_f32_e32 v190, v190, v70
	v_add_f32_e32 v191, v191, v71
	s_waitcnt vmcnt(6)
	v_add_f32_e32 v188, v188, v72
	v_add_f32_e32 v189, v189, v73
	v_add_f32_e32 v190, v190, v74
	v_add_f32_e32 v191, v191, v75
	s_waitcnt vmcnt(4)
	v_add_f32_e32 v188, v188, v76
	v_add_f32_e32 v189, v189, v77
	v_add_f32_e32 v190, v190, v78
	v_add_f32_e32 v191, v191, v79
	s_waitcnt vmcnt(2)
	v_add_f32_e32 v188, v188, v80
	v_add_f32_e32 v189, v189, v81
	v_add_f32_e32 v190, v190, v82
	v_add_f32_e32 v191, v191, v83
	s_waitcnt vmcnt(0)
; __device__ __forceinline__ void phase_rowpass(const Ctx& p, const float* F, int base_is_x, float alpha, const float* gpost, const float* gnext, bf16_t* XN, const float* PART, int nsplit) {
;     ...
;         for (int j = 0; j < 4; ++j) { b[j] = br[64 * j];
;             if (m < MPR) f[j] = fr[64 * j];
;             else { f[j] = (f32x4){0.f, 0.f, 0.f, 0.f};
;                 for (int ks = 0; ks < nsplit; ++ks) f[j] = f[j] + ((const f32x4*)(PART + ((size_t)ks * 128 + (m - MPR)) * DM))[lane + 64 * j]; } }
	v_add_f32_e32 v188, v188, v84
	v_add_f32_e32 v189, v189, v85
	v_add_f32_e32 v190, v190, v86
	v_add_f32_e32 v191, v191, v87
	s_mov_b32 s34, s24
	s_mov_b32 s35, s25
	global_load_dwordx4 v[0:3], v144, s[34:35] offset:2048
	global_load_dwordx4 v[44:47], v144, s[34:35] offset:3072
	s_add_u32 s34, s34, 0x80000
	s_addc_u32 s35, s35, 0
	global_load_dwordx4 v[4:7], v144, s[34:35] offset:2048
	global_load_dwordx4 v[48:51], v144, s[34:35] offset:3072
	s_add_u32 s34, s34, 0x80000
	s_addc_u32 s35, s35, 0
	global_load_dwordx4 v[8:11], v144, s[34:35] offset:2048
	global_load_dwordx4 v[52:55], v144, s[34:35] offset:3072
	s_add_u32 s34, s34, 0x80000
	s_addc_u32 s35, s35, 0
	global_load_dwordx4 v[12:15], v144, s[34:35] offset:2048
	global_load_dwordx4 v[56:59], v144, s[34:35] offset:3072
	s_add_u32 s34, s34, 0x80000
	s_addc_u32 s35, s35, 0
	global_load_dwordx4 v[16:19], v144, s[34:35] offset:2048
	global_load_dwordx4 v[60:63], v144, s[34:35] offset:3072
	s_add_u32 s34, s34, 0x80000
	s_addc_u32 s35, s35, 0
	global_load_dwordx4 v[20:23], v144, s[34:35] offset:2048
	global_load_dwordx4 v[64:67], v144, s[34:35] offset:3072
	s_add_u32 s34, s34, 0x80000
	s_addc_u32 s35, s35, 0
	global_load_dwordx4 v[24:27], v144, s[34:35] offset:2048
	global_load_dwordx4 v[68:71], v144, s[34:35] offset:3072
	s_add_u32 s34, s34, 0x80000
	s_addc_u32 s35, s35, 0
	global_load_dwordx4 v[28:31], v144, s[34:35] offset:2048
	global_load_dwordx4 v[72:75], v144, s[34:35] offset:3072
	s_add_u32 s34, s34, 0x80000
	s_addc_u32 s35, s35, 0
	global_load_dwordx4 v[32:35], v144, s[34:35] offset:2048
	global_load_dwordx4 v[76:79], v144, s[34:35] offset:3072
	s_add_u32 s34, s34, 0x80000
	s_addc_u32 s35, s35, 0
	global_load_dwordx4 v[36:39], v144, s[34:35] offset:2048
	global_load_dwordx4 v[80:83], v144, s[34:35] offset:3072
	s_add_u32 s34, s34, 0x80000
	s_addc_u32 s35, s35, 0
	global_load_dwordx4 v[40:43], v144, s[34:35] offset:2048
	global_load_dwordx4 v[84:87], v144, s[34:35] offset:3072
	s_waitcnt vmcnt(21)
	v_mov_b32_e32 v192, v0
	v_mov_b32_e32 v193, v1
	v_mov_b32_e32 v194, v2
	v_mov_b32_e32 v195, v3
	s_waitcnt vmcnt(19)
	v_add_f32_e32 v192, v192, v4
	v_add_f32_e32 v193, v193, v5
	v_add_f32_e32 v194, v194, v6
	v_add_f32_e32 v195, v195, v7
	s_waitcnt vmcnt(17)
	v_add_f32_e32 v192, v192, v8
	v_add_f32_e32 v193, v193, v9
	v_add_f32_e32 v194, v194, v10
	v_add_f32_e32 v195, v195, v11
	s_waitcnt vmcnt(15)
	v_add_f32_e32 v192, v192, v12
	v_add_f32_e32 v193, v193, v13
	v_add_f32_e32 v194, v194, v14
	v_add_f32_e32 v195, v195, v15
	s_waitcnt vmcnt(13)
	v_add_f32_e32 v192, v192, v16
	v_add_f32_e32 v193, v193, v17
	v_add_f32_e32 v194, v194, v18
	v_add_f32_e32 v195, v195, v19
	s_waitcnt vmcnt(11)
	v_add_f32_e32 v192, v192, v20
	v_add_f32_e32 v193, v193, v21
	v_add_f32_e32 v194, v194, v22
	v_add_f32_e32 v195, v195, v23
	s_waitcnt vmcnt(9)
	v_add_f32_e32 v192, v192, v24
	v_add_f32_e32 v193, v193, v25
	v_add_f32_e32 v194, v194, v26
	v_add_f32_e32 v195, v195, v27
	s_waitcnt vmcnt(7)
	v_add_f32_e32 v192, v192, v28
	v_add_f32_e32 v193, v193, v29
	v_add_f32_e32 v194, v194, v30
	v_add_f32_e32 v195, v195, v31
	s_waitcnt vmcnt(5)
	v_add_f32_e32 v192, v192, v32
	v_add_f32_e32 v193, v193, v33
	v_add_f32_e32 v194, v194, v34
	v_add_f32_e32 v195, v195, v35
	s_waitcnt vmcnt(3)
	v_add_f32_e32 v192, v192, v36
	v_add_f32_e32 v193, v193, v37
	v_add_f32_e32 v194, v194, v38
	v_add_f32_e32 v195, v195, v39
	s_waitcnt vmcnt(1)
	v_add_f32_e32 v192, v192, v40
	v_add_f32_e32 v193, v193, v41
	v_add_f32_e32 v194, v194, v42
	v_add_f32_e32 v195, v195, v43
	s_waitcnt vmcnt(20)
	v_mov_b32_e32 v196, v44
	v_mov_b32_e32 v197, v45
	v_mov_b32_e32 v198, v46
	v_mov_b32_e32 v199, v47
	s_waitcnt vmcnt(18)
	v_add_f32_e32 v196, v196, v48
	v_add_f32_e32 v197, v197, v49
	v_add_f32_e32 v198, v198, v50
	v_add_f32_e32 v199, v199, v51
	s_waitcnt vmcnt(16)
	v_add_f32_e32 v196, v196, v52
	v_add_f32_e32 v197, v197, v53
	v_add_f32_e32 v198, v198, v54
	v_add_f32_e32 v199, v199, v55
	s_waitcnt vmcnt(14)
	v_add_f32_e32 v196, v196, v56
	v_add_f32_e32 v197, v197, v57
	v_add_f32_e32 v198, v198, v58
	v_add_f32_e32 v199, v199, v59
	s_waitcnt vmcnt(12)
	v_add_f32_e32 v196, v196, v60
	v_add_f32_e32 v197, v197, v61
	v_add_f32_e32 v198, v198, v62
	v_add_f32_e32 v199, v199, v63
	s_waitcnt vmcnt(10)
	v_add_f32_e32 v196, v196, v64
	v_add_f32_e32 v197, v197, v65
	v_add_f32_e32 v198, v198, v66
	v_add_f32_e32 v199, v199, v67
	s_waitcnt vmcnt(8)
	v_add_f32_e32 v196, v196, v68
	v_add_f32_e32 v197, v197, v69
	v_add_f32_e32 v198, v198, v70
	v_add_f32_e32 v199, v199, v71
	s_waitcnt vmcnt(6)
	v_add_f32_e32 v196, v196, v72
	v_add_f32_e32 v197, v197, v73
	v_add_f32_e32 v198, v198, v74
	v_add_f32_e32 v199, v199, v75
	s_waitcnt vmcnt(4)
	v_add_f32_e32 v196, v196, v76
	v_add_f32_e32 v197, v197, v77
	v_add_f32_e32 v198, v198, v78
	v_add_f32_e32 v199, v199, v79
	s_waitcnt vmcnt(2)
	v_add_f32_e32 v196, v196, v80
	v_add_f32_e32 v197, v197, v81
	v_add_f32_e32 v198, v198, v82
	v_add_f32_e32 v199, v199, v83
	s_waitcnt vmcnt(0)
	v_add_f32_e32 v196, v196, v84
	v_add_f32_e32 v197, v197, v85
	v_add_f32_e32 v198, v198, v86
	v_add_f32_e32 v199, v199, v87
	s_waitcnt vmcnt(44)
; __device__ __forceinline__ void phase_rowpass(const Ctx& p, const float* F, int base_is_x, float alpha, const float* gpost, const float* gnext, bf16_t* XN, const float* PART, int nsplit) {
;     ...
;         float s = 0.f;
; #pragma unroll
;         for (int j = 0; j < 4; ++j) s += (f[j].x * f[j].x + f[j].y * f[j].y) + (f[j].z * f[j].z + f[j].w * f[j].w);
;         const float rs = alpha / sqrtf(wave_sum_fast(s) * (1.f / DM) + EPS);
;         float s2 = 0.f;
; #pragma unroll
;         for (int j = 0; j < 4; ++j) { b[j] = b[j] + f[j] * rs * gp[j]; s2 += (b[j].x * b[j].x + b[j].y * b[j].y) + (b[j].z * b[j].z + b[j].w * b[j].w);
;             ((f32x4*)(H + (size_t)m * DM))[lane + 64 * j] = b[j]; }
	v_mul_f32_e32 v96, v185, v185
	v_mul_f32_e32 v98, v187, v187
	v_fmac_f32_e32 v96, v184, v184
	v_fmac_f32_e32 v98, v186, v186
	v_add_f32_e32 v96, v96, v98
	v_mul_f32_e32 v97, v189, v189
	v_mul_f32_e32 v98, v191, v191
	v_fmac_f32_e32 v97, v188, v188
	v_fmac_f32_e32 v98, v190, v190
	v_add_f32_e32 v97, v97, v98
	v_add_f32_e32 v96, v97, v96
	v_mul_f32_e32 v97, v193, v193
	v_mul_f32_e32 v98, v195, v195
	v_fmac_f32_e32 v97, v192, v192
	v_fmac_f32_e32 v98, v194, v194
	v_add_f32_e32 v97, v97, v98
	v_add_f32_e32 v96, v97, v96
	v_mul_f32_e32 v97, v197, v197
	v_mul_f32_e32 v98, v199, v199
	v_fmac_f32_e32 v97, v196, v196
	v_fmac_f32_e32 v98, v198, v198
	v_add_f32_e32 v97, v97, v98
	v_add_f32_e32 v96, v97, v96
	s_nop 1
	v_add_f32_dpp v96, v96, v96 quad_perm:[1,0,3,2] row_mask:0xf bank_mask:0xf bound_ctrl:1
	s_nop 1
	v_add_f32_dpp v96, v96, v96 quad_perm:[2,3,0,1] row_mask:0xf bank_mask:0xf bound_ctrl:1
	s_nop 1
	v_add_f32_dpp v96, v96, v96 row_half_mirror row_mask:0xf bank_mask:0xf bound_ctrl:1
	s_nop 1
	v_add_f32_dpp v96, v96, v96 row_mirror row_mask:0xf bank_mask:0xf bound_ctrl:1
	v_mov_b32_e32 v97, v96
	s_nop 1
	v_permlane16_swap_b32_e32 v96, v97
	v_add_f32_e32 v96, v96, v97
	v_mov_b32_e32 v97, v96
	s_nop 1
	v_permlane32_swap_b32_e32 v96, v97
	v_add_f32_e32 v96, v96, v97
	v_fmamk_f32 v96, v96, 0x3a800000, v146
	v_mul_f32_e32 v97, 0x4f800000, v96
	v_cmp_gt_f32_e32 vcc, s33, v96
	s_nop 1
	v_cndmask_b32_e32 v96, v96, v97, vcc
	v_sqrt_f32_e32 v97, v96
	s_nop 0
	v_add_u32_e32 v98, -1, v97
	v_fma_f32 v99, -v98, v97, v96
	v_cmp_ge_f32_e64 s[4:5], 0, v99
	v_add_u32_e32 v99, 1, v97
	s_nop 0
	v_cndmask_b32_e64 v98, v97, v98, s[4:5]
	v_fma_f32 v97, -v99, v97, v96
	v_cmp_lt_f32_e64 s[4:5], 0, v97
	s_nop 1
	v_cndmask_b32_e64 v97, v98, v99, s[4:5]
	v_mul_f32_e32 v98, 0x37800000, v97
	v_cndmask_b32_e32 v97, v97, v98, vcc
	v_cmp_class_f32_e32 vcc, v96, v147
	s_nop 1
	v_cndmask_b32_e32 v96, v97, v96, vcc
	v_div_scale_f32 v97, s[4:5], v96, v96, 0.5
	v_rcp_f32_e32 v98, v97
	s_nop 0
	v_fma_f32 v99, -v97, v98, 1.0
	v_fmac_f32_e32 v98, v99, v98
	v_div_scale_f32 v99, vcc, 0.5, v96, 0.5
	v_mul_f32_e32 v100, v99, v98
	v_fma_f32 v101, -v97, v100, v99
	v_fmac_f32_e32 v100, v101, v98
	v_fma_f32 v97, -v97, v100, v99
	v_div_fmas_f32 v97, v97, v98, v100
	v_div_fixup_f32 v96, v97, v96, 0.5
	v_mul_f32_e32 v184, v184, v96
	v_mul_f32_e32 v185, v185, v96
	v_mul_f32_e32 v186, v186, v96
	v_mul_f32_e32 v187, v187, v96
	v_mul_f32_e32 v188, v188, v96
	v_mul_f32_e32 v189, v189, v96
	v_mul_f32_e32 v190, v190, v96
	v_mul_f32_e32 v191, v191, v96
	v_mul_f32_e32 v192, v192, v96
	v_mul_f32_e32 v193, v193, v96
	v_mul_f32_e32 v194, v194, v96
	v_mul_f32_e32 v195, v195, v96
	v_mul_f32_e32 v196, v196, v96
	v_mul_f32_e32 v197, v197, v96
	v_mul_f32_e32 v198, v198, v96
	v_mul_f32_e32 v199, v199, v96
	v_fmac_f32_e32 v200, v112, v184
	v_fmac_f32_e32 v201, v113, v185
	v_fmac_f32_e32 v202, v114, v186
	v_fmac_f32_e32 v203, v115, v187
	v_fmac_f32_e32 v204, v116, v188
	v_fmac_f32_e32 v205, v117, v189
	v_fmac_f32_e32 v206, v118, v190
	v_fmac_f32_e32 v207, v119, v191
	v_fmac_f32_e32 v208, v120, v192
	v_fmac_f32_e32 v209, v121, v193
	v_fmac_f32_e32 v210, v122, v194
	v_fmac_f32_e32 v211, v123, v195
	v_fmac_f32_e32 v212, v124, v196
	v_fmac_f32_e32 v213, v125, v197
	v_fmac_f32_e32 v214, v126, v198
	v_fmac_f32_e32 v215, v127, v199
	global_store_dwordx4 v144, v[200:203], s[40:41] offset:0
	global_store_dwordx4 v144, v[204:207], s[40:41] offset:1024
	global_store_dwordx4 v144, v[208:211], s[40:41] offset:2048
	global_store_dwordx4 v144, v[212:215], s[40:41] offset:3072
	v_mul_f32_e32 v96, v201, v201
	v_mul_f32_e32 v98, v203, v203
	v_fmac_f32_e32 v96, v200, v200
	v_fmac_f32_e32 v98, v202, v202
; __device__ __forceinline__ unsigned pk2(float lo, float hi) { f32x2 v = {lo, hi}; bf16x2_t b = __builtin_convertvector(v, bf16x2_t); return __builtin_bit_cast(unsigned, b); }
; __device__ __forceinline__ void phase_rowpass(const Ctx& p, const float* F, int base_is_x, float alpha, const float* gpost, const float* gnext, bf16_t* XN, const float* PART, int nsplit) {
;     ...
;         if (gnext) {
;             const float r2 = 1.f / sqrtf(wave_sum_fast(s2) * (1.f / DM) + EPS);
;             u32x2* o8 = (u32x2*)(XN + (size_t)m * DM) + lane;
; #pragma unroll
;             for (int j = 0; j < 4; ++j) { u32x2 w; w.x = pk2(b[j].x * r2 * gn[j].x, b[j].y * r2 * gn[j].y); w.y = pk2(b[j].z * r2 * gn[j].z, b[j].w * r2 * gn[j].w); o8[64 * j] = w; }
	v_add_f32_e32 v96, v96, v98
	v_mul_f32_e32 v97, v205, v205
	v_mul_f32_e32 v98, v207, v207
	v_fmac_f32_e32 v97, v204, v204
	v_fmac_f32_e32 v98, v206, v206
	v_add_f32_e32 v97, v97, v98
	v_add_f32_e32 v96, v97, v96
	v_mul_f32_e32 v97, v209, v209
	v_mul_f32_e32 v98, v211, v211
	v_fmac_f32_e32 v97, v208, v208
	v_fmac_f32_e32 v98, v210, v210
	v_add_f32_e32 v97, v97, v98
	v_add_f32_e32 v96, v97, v96
	v_mul_f32_e32 v97, v213, v213
	v_mul_f32_e32 v98, v215, v215
	v_fmac_f32_e32 v97, v212, v212
	v_fmac_f32_e32 v98, v214, v214
	v_add_f32_e32 v97, v97, v98
	v_add_f32_e32 v96, v97, v96
	s_nop 1
	v_add_f32_dpp v96, v96, v96 quad_perm:[1,0,3,2] row_mask:0xf bank_mask:0xf bound_ctrl:1
	s_nop 1
	v_add_f32_dpp v96, v96, v96 quad_perm:[2,3,0,1] row_mask:0xf bank_mask:0xf bound_ctrl:1
	s_nop 1
	v_add_f32_dpp v96, v96, v96 row_half_mirror row_mask:0xf bank_mask:0xf bound_ctrl:1
	s_nop 1
	v_add_f32_dpp v96, v96, v96 row_mirror row_mask:0xf bank_mask:0xf bound_ctrl:1
	v_mov_b32_e32 v97, v96
	s_nop 1
	v_permlane16_swap_b32_e32 v96, v97
	v_add_f32_e32 v96, v96, v97
	v_mov_b32_e32 v97, v96
	s_nop 1
	v_permlane32_swap_b32_e32 v96, v97
	v_add_f32_e32 v96, v96, v97
	v_fmamk_f32 v96, v96, 0x3a800000, v146
	v_mul_f32_e32 v97, 0x4f800000, v96
	v_cmp_gt_f32_e32 vcc, s33, v96
	s_nop 1
	v_cndmask_b32_e32 v96, v96, v97, vcc
	v_sqrt_f32_e32 v97, v96
	s_nop 0
	v_add_u32_e32 v98, -1, v97
	v_fma_f32 v99, -v98, v97, v96
	v_cmp_ge_f32_e64 s[4:5], 0, v99
	v_add_u32_e32 v99, 1, v97
	s_nop 0
	v_cndmask_b32_e64 v98, v97, v98, s[4:5]
	v_fma_f32 v97, -v99, v97, v96
	v_cmp_lt_f32_e64 s[4:5], 0, v97
	s_nop 1
	v_cndmask_b32_e64 v97, v98, v99, s[4:5]
	v_mul_f32_e32 v98, 0x37800000, v97
	v_cndmask_b32_e32 v97, v97, v98, vcc
	v_cmp_class_f32_e32 vcc, v96, v147
	s_nop 1
	v_cndmask_b32_e32 v96, v97, v96, vcc
	v_div_scale_f32 v97, s[4:5], v96, v96, 1.0
	v_rcp_f32_e32 v98, v97
	s_nop 0
	v_fma_f32 v99, -v97, v98, 1.0
	v_fmac_f32_e32 v98, v99, v98
	v_div_scale_f32 v99, vcc, 1.0, v96, 1.0
	v_mul_f32_e32 v100, v99, v98
	v_fma_f32 v101, -v97, v100, v99
	v_fmac_f32_e32 v100, v101, v98
	v_fma_f32 v97, -v97, v100, v99
	v_div_fmas_f32 v97, v97, v98, v100
	v_div_fixup_f32 v96, v97, v96, 1.0
	v_mul_f32_e32 v184, v200, v96
	v_mul_f32_e32 v185, v201, v96
	v_mul_f32_e32 v186, v202, v96
	v_mul_f32_e32 v187, v203, v96
	v_mul_f32_e32 v188, v204, v96
	v_mul_f32_e32 v189, v205, v96
	v_mul_f32_e32 v190, v206, v96
	v_mul_f32_e32 v191, v207, v96
	v_mul_f32_e32 v192, v208, v96
	v_mul_f32_e32 v193, v209, v96
	v_mul_f32_e32 v194, v210, v96
	v_mul_f32_e32 v195, v211, v96
	v_mul_f32_e32 v196, v212, v96
	v_mul_f32_e32 v197, v213, v96
	v_mul_f32_e32 v198, v214, v96
	v_mul_f32_e32 v199, v215, v96
	v_mul_f32_e32 v184, v128, v184
	v_mul_f32_e32 v185, v129, v185
	v_mul_f32_e32 v186, v130, v186
	v_mul_f32_e32 v187, v131, v187
	v_mul_f32_e32 v188, v132, v188
	v_mul_f32_e32 v189, v133, v189
	v_mul_f32_e32 v190, v134, v190
	v_mul_f32_e32 v191, v135, v191
	v_mul_f32_e32 v192, v136, v192
	v_mul_f32_e32 v193, v137, v193
	v_mul_f32_e32 v194, v138, v194
	v_mul_f32_e32 v195, v139, v195
	v_mul_f32_e32 v196, v140, v196
	v_mul_f32_e32 v197, v141, v197
	v_mul_f32_e32 v198, v142, v198
	v_mul_f32_e32 v199, v143, v199
	v_cvt_pk_bf16_f32 v148, v184, v185
	v_cvt_pk_bf16_f32 v149, v186, v187
	global_store_dwordx2 v145, v[148:149], s[42:43] offset:0
	v_cvt_pk_bf16_f32 v150, v188, v189
	v_cvt_pk_bf16_f32 v151, v190, v191
	global_store_dwordx2 v145, v[150:151], s[42:43] offset:512
	v_cvt_pk_bf16_f32 v152, v192, v193
	v_cvt_pk_bf16_f32 v153, v194, v195
	global_store_dwordx2 v145, v[152:153], s[42:43] offset:1024
	v_cvt_pk_bf16_f32 v154, v196, v197
	v_cvt_pk_bf16_f32 v155, v198, v199
	global_store_dwordx2 v145, v[154:155], s[42:43] offset:1536
